# adaLN modulation k-loop hand-rewritten (all loads up front, counted waits) + XCD-contiguous column-block remap, on top of rcp sigmoid
# speedup vs baseline: 1.0096x; 1.0096x over previous
; __device__ __forceinline__ void phase_prologue(const Frame& F) {
;     ...
;         const float* cp = F.in[2]; const float* cs = F.in[3]; const float* wada = F.in[8]; const float* bada = F.in[9];
;         const int cgp = tid % 12, cdg = (tid / 12) % 4, kl = tid / 48;
;         for (int cb = F.bid; cb < 256; cb += F.G) {
;             typedef float f32x2 __attribute__((ext_vector_type(2)));
;             f32x2 acc[12][2];
; #pragma unroll
;             for (int c = 0; c < 12; ++c) { acc[c][0] = (f32x2){0.f, 0.f}; acc[c][1] = (f32x2){0.f, 0.f}; }
;             for (int kc = 0; kc < 8; ++kc) {
;                 __syncthreads();
;                 for (int i = 0; i < 24; ++i) { const int idx = tid + 512 * i, cd = idx >> 8, kk = idx & 255;
.LBB0_7:
	s_load_dwordx16 s[44:59], s[0:1], 0x0
	s_load_dwordx16 s[4:19], s[0:1], 0x80
	s_cmp_lt_i32 s96, 1
	s_cselect_b64 s[0:1], -1, 0
	s_cmp_gt_i32 s97, 0
	s_cselect_b64 s[2:3], -1, 0
	s_waitcnt lgkmcnt(0)
	v_writelane_b32 v254, s4, 5
	s_and_b64 s[0:1], s[0:1], s[2:3]
	s_nop 0
	v_writelane_b32 v254, s5, 6
	v_writelane_b32 v254, s6, 7
	v_writelane_b32 v254, s7, 8
	v_writelane_b32 v254, s8, 9
	v_writelane_b32 v254, s9, 10
	v_writelane_b32 v254, s10, 11
	v_writelane_b32 v254, s11, 12
	v_writelane_b32 v254, s12, 13
	v_writelane_b32 v254, s13, 14
	v_writelane_b32 v254, s14, 15
	v_writelane_b32 v254, s15, 16
	v_writelane_b32 v254, s16, 17
	v_writelane_b32 v254, s17, 18
	v_writelane_b32 v254, s18, 19
	v_writelane_b32 v254, s19, 20
	v_writelane_b32 v254, s0, 21
	s_andn2_b64 vcc, exec, s[0:1]
	s_nop 0
	v_writelane_b32 v254, s1, 22
	s_cbranch_vccnz .LBB0_131
	s_cmpk_gt_i32 s94, 0xff
	s_cbranch_scc1 .LBB0_25
	v_mul_u32_u24_e32 v1, 0x556, v192
	v_mul_u32_u24_e32 v2, 0x1556, v192
	v_lshrrev_b32_e32 v1, 16, v1
	v_bfe_u32 v3, v2, 16, 2
	v_mul_u32_u24_e32 v4, 0x900, v3
	v_mad_u32_u24 v65, v3, 48, 0
	v_sub_u32_e32 v3, 0xf5, v1
	s_mov_b32 s3, 0x1999999a
	v_mul_hi_u32 v3, v3, s3
	v_and_b32_e32 v3, 1, v3
	v_mov_b32_e32 v6, 12
	v_cmp_eq_u32_e64 s[4:5], 1, v3
	v_add_u32_e32 v3, 0x600, v192
	v_mul_lo_u16_sdwa v2, v2, v6 dst_sel:DWORD dst_unused:UNUSED_PAD src0_sel:WORD_1 src1_sel:DWORD
	v_lshrrev_b32_e32 v3, 8, v3
	v_sub_u16_e32 v2, v192, v2
	s_movk_i32 s2, 0xd0
	v_lshlrev_b32_e32 v7, 2, v3
	v_lshlrev_b32_e32 v68, 11, v3
	v_add_u32_e32 v3, 0x200, v192
	v_lshlrev_b32_e32 v50, 4, v2
	v_mul_u32_u24_sdwa v2, v192, s2 dst_sel:DWORD dst_unused:UNUSED_PAD src0_sel:BYTE_0 src1_sel:DWORD
	v_lshrrev_b32_e32 v3, 8, v3
	v_mov_b32_e32 v51, 0
	v_add3_u32 v67, v2, v7, 0
	v_lshlrev_b32_e32 v7, 2, v3
	v_lshlrev_b32_e32 v70, 11, v3
	v_lshrrev_b32_e32 v3, 8, v192
	s_movk_i32 s0, 0x8000
	v_lshl_add_u64 v[52:53], s[76:77], 0, v[50:51]
	v_add3_u32 v4, 0, v50, v4
	v_add3_u32 v69, v2, v7, 0
	v_lshl_or_b32 v2, v3, 2, v2
	v_lshlrev_b32_e32 v50, 2, v192
	v_or_b32_sdwa v64, v192, s0 dst_sel:DWORD dst_unused:UNUSED_PAD src0_sel:BYTE_0 src1_sel:DWORD
	s_movk_i32 s0, 0x1e0
	v_mul_u32_u24_e32 v5, 0x2400, v1
	v_mul_u32_u24_e32 v6, 0xd0, v1
	v_lshlrev_b32_e32 v71, 11, v3
	v_add_u32_e32 v72, 0, v2
	v_lshl_add_u64 v[2:3], s[66:67], 0, v[50:51]
	s_mov_b64 s[6:7], 0x4000
	v_cmp_gt_u32_e64 s[0:1], s0, v192
	v_add_u32_e32 v66, 10, v1
	s_mul_i32 s14, s94, 48
	v_add_u32_e32 v73, 0, v50
	v_mov_b32_e32 v193, v51
	v_lshl_add_u64 v[54:55], v[2:3], 0, s[6:7]
	s_movk_i32 s3, 0x1000
	s_mov_b32 s24, 0xc000
	v_add_u32_e32 v74, v65, v6
	s_mov_b64 s[16:17], 0xf0000
	v_add_u32_e32 v75, v4, v5
	s_mov_b32 s25, 0xaaaaaaab
	s_mov_b32 s26, 0xaaaaaaaa
	s_mov_b32 s27, 0xbf40
	s_mov_b64 s[18:19], 0x800
	s_movk_i32 s28, 0x6ff
	s_mov_b32 s29, s94
	s_cmp_lg_u32 s92, 0x100
	s_cbranch_scc1 .Lmod_noremap
	s_and_b32 s6, s94, 7
	s_lshl_b32 s6, s6, 5
	s_lshr_b32 s7, s94, 3
	s_or_b32 s29, s6, s7
	s_mul_i32 s14, s29, 48
.Lmod_noremap:
.LBB0_10:
	s_ashr_i32 s15, s14, 31
	s_mul_i32 s6, s29, 48
	s_lshl_b64 s[20:21], s[14:15], 2
	s_ashr_i32 s7, s6, 31
	v_mov_b32_e32 v50, v51
	v_lshl_add_u64 v[56:57], s[6:7], 2, v[52:53]
	v_lshl_add_u64 v[58:59], v[52:53], 0, s[20:21]
	s_mov_b64 s[22:23], 0
	s_mov_b32 s15, 10
	v_mov_b64_e32 v[32:33], v[50:51]
	v_mov_b64_e32 v[30:31], v[50:51]
	v_mov_b64_e32 v[40:41], v[50:51]
	v_mov_b64_e32 v[38:39], v[50:51]
	v_mov_b64_e32 v[44:45], v[50:51]
	v_mov_b64_e32 v[42:43], v[50:51]
	v_mov_b64_e32 v[48:49], v[50:51]
	v_mov_b64_e32 v[46:47], v[50:51]
	v_mov_b64_e32 v[34:35], v[50:51]
	v_mov_b64_e32 v[36:37], v[50:51]
	v_mov_b64_e32 v[26:27], v[50:51]
	v_mov_b64_e32 v[28:29], v[50:51]
	v_mov_b64_e32 v[22:23], v[50:51]
	v_mov_b64_e32 v[24:25], v[50:51]
	v_mov_b64_e32 v[18:19], v[50:51]
	v_mov_b64_e32 v[20:21], v[50:51]
	v_mov_b64_e32 v[14:15], v[50:51]
	v_mov_b64_e32 v[16:17], v[50:51]
	v_mov_b64_e32 v[10:11], v[50:51]
	v_mov_b64_e32 v[12:13], v[50:51]
	v_mov_b64_e32 v[6:7], v[50:51]
	v_mov_b64_e32 v[8:9], v[50:51]
	v_mov_b64_e32 v[2:3], v[50:51]
	v_mov_b64_e32 v[4:5], v[50:51]
	v_lshrrev_b32_e32 v78, 8, v192
	v_and_b32_e32 v79, 0xff, v192
	v_lshlrev_b32_e32 v76, 13, v78
	v_lshl_or_b32 v76, v79, 2, v76
	v_mul_u32_u24_e32 v77, 0xd0, v79
	v_lshl_add_u32 v77, v78, 2, v77
	v_mov_b32_e32 v236, 0x78000
	v_mov_b32_e32 v237, 0
	v_cndmask_b32_e64 v236, v236, 0, s[4:5]
	s_mov_b32 s12, 0x78000
	s_mov_b32 s13, 0
	s_mov_b32 s30, 0
; __device__ __forceinline__ float sigmoidf_(float x) { return 1.0f / (1.0f + __expf(-x)); }
; __device__ __forceinline__ void phase_prologue(const Frame& F) {
;     ...
;                 __syncthreads();
;                 for (int i = 0; i < 24; ++i) { const int idx = tid + 512 * i, cd = idx >> 8, kk = idx & 255;
;                     const float cv = cd < 16 ? cp[cd * D + kc * 256 + kk] : cs[(cd - 16) * D + kc * 256 + kk];
;                     sT[kk * 52 + cd] = cv * sigmoidf_(cv); }
;                 __syncthreads();
;                 if (tid < 480) {
; #pragma unroll 2
;                     for (int kk = kl; kk < 256; kk += 10) {
;                         const f32x4 w4 = *(const f32x4*)(wada + (size_t)(kc * 256 + kk) * MODW + 48 * cb + 4 * cgp);
.Lmod_kc:
	s_lshl_b32 s31, s30, 8
	s_lshl_b32 s6, s30, 10
	s_add_u32 s8, s48, s6
	s_addc_u32 s9, s49, 0
	global_load_dword v80, v76, s[8:9]
	s_add_u32 s8, s8, 0x4000
	s_addc_u32 s9, s9, 0
	global_load_dword v81, v76, s[8:9]
	s_add_u32 s8, s8, 0x4000
	s_addc_u32 s9, s9, 0
	global_load_dword v82, v76, s[8:9]
	s_add_u32 s8, s8, 0x4000
	s_addc_u32 s9, s9, 0
	global_load_dword v83, v76, s[8:9]
	s_add_u32 s8, s8, 0x4000
	s_addc_u32 s9, s9, 0
	global_load_dword v84, v76, s[8:9]
	s_add_u32 s8, s8, 0x4000
	s_addc_u32 s9, s9, 0
	global_load_dword v85, v76, s[8:9]
	s_add_u32 s8, s8, 0x4000
	s_addc_u32 s9, s9, 0
	global_load_dword v86, v76, s[8:9]
	s_add_u32 s8, s8, 0x4000
	s_addc_u32 s9, s9, 0
	global_load_dword v87, v76, s[8:9]
	s_add_u32 s8, s50, s6
	s_addc_u32 s9, s51, 0
	global_load_dword v88, v76, s[8:9]
	s_add_u32 s8, s8, 0x4000
	s_addc_u32 s9, s9, 0
	global_load_dword v89, v76, s[8:9]
	s_add_u32 s8, s8, 0x4000
	s_addc_u32 s9, s9, 0
	global_load_dword v90, v76, s[8:9]
	s_add_u32 s8, s8, 0x4000
	s_addc_u32 s9, s9, 0
	global_load_dword v91, v76, s[8:9]
	s_add_u32 s8, s8, 0x4000
	s_addc_u32 s9, s9, 0
	global_load_dword v92, v76, s[8:9]
	s_add_u32 s8, s8, 0x4000
	s_addc_u32 s9, s9, 0
	global_load_dword v93, v76, s[8:9]
	s_add_u32 s8, s8, 0x4000
	s_addc_u32 s9, s9, 0
	global_load_dword v94, v76, s[8:9]
	s_add_u32 s8, s8, 0x4000
	s_addc_u32 s9, s9, 0
	global_load_dword v95, v76, s[8:9]
	s_add_u32 s8, s8, 0x4000
	s_addc_u32 s9, s9, 0
	global_load_dword v96, v76, s[8:9]
	s_add_u32 s8, s8, 0x4000
	s_addc_u32 s9, s9, 0
	global_load_dword v97, v76, s[8:9]
	s_add_u32 s8, s8, 0x4000
	s_addc_u32 s9, s9, 0
	global_load_dword v98, v76, s[8:9]
	s_add_u32 s8, s8, 0x4000
	s_addc_u32 s9, s9, 0
	global_load_dword v99, v76, s[8:9]
	s_add_u32 s8, s8, 0x4000
	s_addc_u32 s9, s9, 0
	global_load_dword v100, v76, s[8:9]
	s_add_u32 s8, s8, 0x4000
	s_addc_u32 s9, s9, 0
	global_load_dword v101, v76, s[8:9]
	s_add_u32 s8, s8, 0x4000
	s_addc_u32 s9, s9, 0
	global_load_dword v102, v76, s[8:9]
	s_add_u32 s8, s8, 0x4000
	s_addc_u32 s9, s9, 0
	global_load_dword v103, v76, s[8:9]
	s_and_saveexec_b64 s[10:11], s[0:1]
	v_or_b32_e32 v78, s31, v1
	v_mad_u64_u32 v[234:235], s[6:7], v78, s24, v[58:59]
	global_load_dwordx4 v[104:107], v[234:235], off
	v_lshl_add_u64 v[234:235], v[234:235], 0, s[12:13]
	global_load_dwordx4 v[108:111], v[234:235], off
	v_lshl_add_u64 v[234:235], v[234:235], 0, s[12:13]
	global_load_dwordx4 v[112:115], v[234:235], off
	v_lshl_add_u64 v[234:235], v[234:235], 0, s[12:13]
	global_load_dwordx4 v[116:119], v[234:235], off
	v_lshl_add_u64 v[234:235], v[234:235], 0, s[12:13]
	global_load_dwordx4 v[120:123], v[234:235], off
	v_lshl_add_u64 v[234:235], v[234:235], 0, s[12:13]
	global_load_dwordx4 v[124:127], v[234:235], off
	v_lshl_add_u64 v[234:235], v[234:235], 0, s[12:13]
	global_load_dwordx4 v[128:131], v[234:235], off
	v_lshl_add_u64 v[234:235], v[234:235], 0, s[12:13]
	global_load_dwordx4 v[132:135], v[234:235], off
	v_lshl_add_u64 v[234:235], v[234:235], 0, s[12:13]
	global_load_dwordx4 v[136:139], v[234:235], off
	v_lshl_add_u64 v[234:235], v[234:235], 0, s[12:13]
	global_load_dwordx4 v[140:143], v[234:235], off
	v_lshl_add_u64 v[234:235], v[234:235], 0, s[12:13]
	global_load_dwordx4 v[144:147], v[234:235], off
	v_lshl_add_u64 v[234:235], v[234:235], 0, s[12:13]
	global_load_dwordx4 v[148:151], v[234:235], off
	v_lshl_add_u64 v[234:235], v[234:235], 0, s[12:13]
	global_load_dwordx4 v[152:155], v[234:235], off
	v_lshl_add_u64 v[234:235], v[234:235], 0, s[12:13]
	global_load_dwordx4 v[156:159], v[234:235], off
	v_lshl_add_u64 v[234:235], v[234:235], 0, s[12:13]
	global_load_dwordx4 v[160:163], v[234:235], off
	v_lshl_add_u64 v[234:235], v[234:235], 0, s[12:13]
	global_load_dwordx4 v[164:167], v[234:235], off
	v_lshl_add_u64 v[234:235], v[234:235], 0, s[12:13]
	global_load_dwordx4 v[168:171], v[234:235], off
	v_lshl_add_u64 v[234:235], v[234:235], 0, s[12:13]
	global_load_dwordx4 v[172:175], v[234:235], off
	v_lshl_add_u64 v[234:235], v[234:235], 0, s[12:13]
	global_load_dwordx4 v[176:179], v[234:235], off
	v_lshl_add_u64 v[234:235], v[234:235], 0, s[12:13]
	global_load_dwordx4 v[180:183], v[234:235], off
	v_lshl_add_u64 v[234:235], v[234:235], 0, s[12:13]
	global_load_dwordx4 v[184:187], v[234:235], off
	v_lshl_add_u64 v[234:235], v[234:235], 0, s[12:13]
	global_load_dwordx4 v[188:191], v[234:235], off
	v_lshl_add_u64 v[234:235], v[234:235], 0, s[12:13]
	global_load_dwordx4 v[194:197], v[234:235], off
	v_lshl_add_u64 v[234:235], v[234:235], 0, s[12:13]
	global_load_dwordx4 v[198:201], v[234:235], off
	v_lshl_add_u64 v[234:235], v[234:235], 0, s[12:13]
	global_load_dwordx4 v[202:205], v[234:235], off
	v_lshl_add_u64 v[234:235], v[234:235], 0, v[236:237]
	global_load_dwordx4 v[206:209], v[234:235], off
	s_mov_b64 exec, s[10:11]
	s_barrier
; __device__ __forceinline__ float sigmoidf_(float x) { return 1.0f / (1.0f + __expf(-x)); }
; __device__ __forceinline__ void phase_prologue(const Frame& F) {
;     ...
;                 __syncthreads();
;                 for (int i = 0; i < 24; ++i) { const int idx = tid + 512 * i, cd = idx >> 8, kk = idx & 255;
;                     const float cv = cd < 16 ? cp[cd * D + kc * 256 + kk] : cs[(cd - 16) * D + kc * 256 + kk];
;                     sT[kk * 52 + cd] = cv * sigmoidf_(cv); }
;                 __syncthreads();
	s_waitcnt vmcnt(26)
	v_mul_f32_e32 v210, 0xbfb8aa3b, v80
	v_mul_f32_e32 v211, 0xbfb8aa3b, v81
	v_mul_f32_e32 v212, 0xbfb8aa3b, v82
	v_mul_f32_e32 v213, 0xbfb8aa3b, v83
	v_exp_f32_e32 v210, v210
	v_exp_f32_e32 v211, v211
	v_exp_f32_e32 v212, v212
	v_exp_f32_e32 v213, v213
	v_add_f32_e32 v210, 1.0, v210
	v_add_f32_e32 v211, 1.0, v211
	v_add_f32_e32 v212, 1.0, v212
	v_add_f32_e32 v213, 1.0, v213
	v_rcp_f32_e32 v210, v210
	v_rcp_f32_e32 v211, v211
	v_rcp_f32_e32 v212, v212
	v_rcp_f32_e32 v213, v213
	v_mul_f32_e32 v210, v80, v210
	v_mul_f32_e32 v211, v81, v211
	v_mul_f32_e32 v212, v82, v212
	v_mul_f32_e32 v213, v83, v213
	ds_write_b32 v77, v210 offset:0
	ds_write_b32 v77, v211 offset:8
	ds_write_b32 v77, v212 offset:16
	ds_write_b32 v77, v213 offset:24
	v_mul_f32_e32 v214, 0xbfb8aa3b, v84
	v_mul_f32_e32 v215, 0xbfb8aa3b, v85
	v_mul_f32_e32 v216, 0xbfb8aa3b, v86
	v_mul_f32_e32 v217, 0xbfb8aa3b, v87
	v_exp_f32_e32 v214, v214
	v_exp_f32_e32 v215, v215
	v_exp_f32_e32 v216, v216
	v_exp_f32_e32 v217, v217
	v_add_f32_e32 v214, 1.0, v214
	v_add_f32_e32 v215, 1.0, v215
	v_add_f32_e32 v216, 1.0, v216
	v_add_f32_e32 v217, 1.0, v217
	v_rcp_f32_e32 v214, v214
	v_rcp_f32_e32 v215, v215
	v_rcp_f32_e32 v216, v216
	v_rcp_f32_e32 v217, v217
	v_mul_f32_e32 v214, v84, v214
	v_mul_f32_e32 v215, v85, v215
	v_mul_f32_e32 v216, v86, v216
	v_mul_f32_e32 v217, v87, v217
	ds_write_b32 v77, v214 offset:32
	ds_write_b32 v77, v215 offset:40
	ds_write_b32 v77, v216 offset:48
	ds_write_b32 v77, v217 offset:56
	v_mul_f32_e32 v218, 0xbfb8aa3b, v88
	v_mul_f32_e32 v219, 0xbfb8aa3b, v89
	v_mul_f32_e32 v220, 0xbfb8aa3b, v90
	v_mul_f32_e32 v221, 0xbfb8aa3b, v91
	v_exp_f32_e32 v218, v218
	v_exp_f32_e32 v219, v219
	v_exp_f32_e32 v220, v220
	v_exp_f32_e32 v221, v221
	v_add_f32_e32 v218, 1.0, v218
	v_add_f32_e32 v219, 1.0, v219
	v_add_f32_e32 v220, 1.0, v220
	v_add_f32_e32 v221, 1.0, v221
	v_rcp_f32_e32 v218, v218
	v_rcp_f32_e32 v219, v219
	v_rcp_f32_e32 v220, v220
	v_rcp_f32_e32 v221, v221
	v_mul_f32_e32 v218, v88, v218
	v_mul_f32_e32 v219, v89, v219
	v_mul_f32_e32 v220, v90, v220
	v_mul_f32_e32 v221, v91, v221
	ds_write_b32 v77, v218 offset:64
	ds_write_b32 v77, v219 offset:72
	ds_write_b32 v77, v220 offset:80
	ds_write_b32 v77, v221 offset:88
	v_mul_f32_e32 v222, 0xbfb8aa3b, v92
	v_mul_f32_e32 v223, 0xbfb8aa3b, v93
	v_mul_f32_e32 v224, 0xbfb8aa3b, v94
	v_mul_f32_e32 v225, 0xbfb8aa3b, v95
	v_exp_f32_e32 v222, v222
	v_exp_f32_e32 v223, v223
	v_exp_f32_e32 v224, v224
	v_exp_f32_e32 v225, v225
	v_add_f32_e32 v222, 1.0, v222
	v_add_f32_e32 v223, 1.0, v223
	v_add_f32_e32 v224, 1.0, v224
	v_add_f32_e32 v225, 1.0, v225
	v_rcp_f32_e32 v222, v222
	v_rcp_f32_e32 v223, v223
	v_rcp_f32_e32 v224, v224
	v_rcp_f32_e32 v225, v225
	v_mul_f32_e32 v222, v92, v222
	v_mul_f32_e32 v223, v93, v223
	v_mul_f32_e32 v224, v94, v224
	v_mul_f32_e32 v225, v95, v225
	ds_write_b32 v77, v222 offset:96
	ds_write_b32 v77, v223 offset:104
	ds_write_b32 v77, v224 offset:112
	ds_write_b32 v77, v225 offset:120
	v_mul_f32_e32 v226, 0xbfb8aa3b, v96
	v_mul_f32_e32 v227, 0xbfb8aa3b, v97
	v_mul_f32_e32 v228, 0xbfb8aa3b, v98
	v_mul_f32_e32 v229, 0xbfb8aa3b, v99
	v_exp_f32_e32 v226, v226
	v_exp_f32_e32 v227, v227
	v_exp_f32_e32 v228, v228
	v_exp_f32_e32 v229, v229
	v_add_f32_e32 v226, 1.0, v226
	v_add_f32_e32 v227, 1.0, v227
	v_add_f32_e32 v228, 1.0, v228
	v_add_f32_e32 v229, 1.0, v229
	v_rcp_f32_e32 v226, v226
	v_rcp_f32_e32 v227, v227
	v_rcp_f32_e32 v228, v228
	v_rcp_f32_e32 v229, v229
	v_mul_f32_e32 v226, v96, v226
	v_mul_f32_e32 v227, v97, v227
	v_mul_f32_e32 v228, v98, v228
	v_mul_f32_e32 v229, v99, v229
	ds_write_b32 v77, v226 offset:128
	ds_write_b32 v77, v227 offset:136
	ds_write_b32 v77, v228 offset:144
	ds_write_b32 v77, v229 offset:152
	v_mul_f32_e32 v230, 0xbfb8aa3b, v100
	v_mul_f32_e32 v231, 0xbfb8aa3b, v101
	v_mul_f32_e32 v232, 0xbfb8aa3b, v102
	v_mul_f32_e32 v233, 0xbfb8aa3b, v103
	v_exp_f32_e32 v230, v230
	v_exp_f32_e32 v231, v231
	v_exp_f32_e32 v232, v232
	v_exp_f32_e32 v233, v233
	v_add_f32_e32 v230, 1.0, v230
	v_add_f32_e32 v231, 1.0, v231
	v_add_f32_e32 v232, 1.0, v232
	v_add_f32_e32 v233, 1.0, v233
	v_rcp_f32_e32 v230, v230
	v_rcp_f32_e32 v231, v231
	v_rcp_f32_e32 v232, v232
	v_rcp_f32_e32 v233, v233
	v_mul_f32_e32 v230, v100, v230
	v_mul_f32_e32 v231, v101, v231
	v_mul_f32_e32 v232, v102, v232
	v_mul_f32_e32 v233, v103, v233
	ds_write_b32 v77, v230 offset:160
	ds_write_b32 v77, v231 offset:168
	ds_write_b32 v77, v232 offset:176
	ds_write_b32 v77, v233 offset:184
	s_waitcnt lgkmcnt(0)
	s_barrier
; #define LAS __attribute__((address_space(3)))
; __device__ __forceinline__ void phase_prologue(const Frame& F) {
;     ...
;                 if (tid < 480) {
; #pragma unroll 2
;                     for (int kk = kl; kk < 256; kk += 10) {
;                         const f32x4 w4 = *(const f32x4*)(wada + (size_t)(kc * 256 + kk) * MODW + 48 * cb + 4 * cgp);
;                         const f32x2 w01 = (f32x2){w4[0], w4[1]}, w23 = (f32x2){w4[2], w4[3]};
;                         const LAS f32x4* sp = (const LAS f32x4*)(sT + kk * 52 + 12 * cdg);
;                         const f32x4 s0 = sp[0], s1 = sp[1], s2 = sp[2];
; #pragma unroll
;                         for (int c = 0; c < 4; ++c) {
;                             acc[c][0] = __builtin_elementwise_fma((f32x2){s0[c], s0[c]}, w01, acc[c][0]); acc[c][1] = __builtin_elementwise_fma((f32x2){s0[c], s0[c]}, w23, acc[c][1]);
;                             acc[4 + c][0] = __builtin_elementwise_fma((f32x2){s1[c], s1[c]}, w01, acc[4 + c][0]); acc[4 + c][1] = __builtin_elementwise_fma((f32x2){s1[c], s1[c]}, w23, acc[4 + c][1]);
;                             acc[8 + c][0] = __builtin_elementwise_fma((f32x2){s2[c], s2[c]}, w01, acc[8 + c][0]); acc[8 + c][1] = __builtin_elementwise_fma((f32x2){s2[c], s2[c]}, w23, acc[8 + c][1]); }
;                     }
	s_and_saveexec_b64 s[10:11], s[0:1]
	ds_read_b128 v[210:213], v74 offset:0
	ds_read_b128 v[214:217], v74 offset:16
	ds_read_b128 v[218:221], v74 offset:32
	ds_read_b128 v[222:225], v74 offset:2080
	ds_read_b128 v[226:229], v74 offset:2096
	ds_read_b128 v[230:233], v74 offset:2112
	s_waitcnt vmcnt(25) lgkmcnt(3)
	v_pk_fma_f32 v[46:47], v[210:211], v[104:105], v[46:47] op_sel_hi:[0,1,1]
	v_pk_fma_f32 v[48:49], v[210:211], v[106:107], v[48:49] op_sel_hi:[0,1,1]
	v_pk_fma_f32 v[34:35], v[214:215], v[104:105], v[34:35] op_sel_hi:[0,1,1]
	v_pk_fma_f32 v[36:37], v[214:215], v[106:107], v[36:37] op_sel_hi:[0,1,1]
	v_pk_fma_f32 v[14:15], v[218:219], v[104:105], v[14:15] op_sel_hi:[0,1,1]
	v_pk_fma_f32 v[16:17], v[218:219], v[106:107], v[16:17] op_sel_hi:[0,1,1]
	v_pk_fma_f32 v[42:43], v[210:211], v[104:105], v[42:43] op_sel:[1,0,0]
	v_pk_fma_f32 v[44:45], v[210:211], v[106:107], v[44:45] op_sel:[1,0,0]
	v_pk_fma_f32 v[26:27], v[214:215], v[104:105], v[26:27] op_sel:[1,0,0]
	v_pk_fma_f32 v[28:29], v[214:215], v[106:107], v[28:29] op_sel:[1,0,0]
	v_pk_fma_f32 v[10:11], v[218:219], v[104:105], v[10:11] op_sel:[1,0,0]
	v_pk_fma_f32 v[12:13], v[218:219], v[106:107], v[12:13] op_sel:[1,0,0]
	v_pk_fma_f32 v[38:39], v[212:213], v[104:105], v[38:39] op_sel_hi:[0,1,1]
	v_pk_fma_f32 v[40:41], v[212:213], v[106:107], v[40:41] op_sel_hi:[0,1,1]
	v_pk_fma_f32 v[22:23], v[216:217], v[104:105], v[22:23] op_sel_hi:[0,1,1]
	v_pk_fma_f32 v[24:25], v[216:217], v[106:107], v[24:25] op_sel_hi:[0,1,1]
	v_pk_fma_f32 v[6:7], v[220:221], v[104:105], v[6:7] op_sel_hi:[0,1,1]
	v_pk_fma_f32 v[8:9], v[220:221], v[106:107], v[8:9] op_sel_hi:[0,1,1]
	v_pk_fma_f32 v[30:31], v[212:213], v[104:105], v[30:31] op_sel:[1,0,0]
	v_pk_fma_f32 v[32:33], v[212:213], v[106:107], v[32:33] op_sel:[1,0,0]
	v_pk_fma_f32 v[18:19], v[216:217], v[104:105], v[18:19] op_sel:[1,0,0]
	v_pk_fma_f32 v[20:21], v[216:217], v[106:107], v[20:21] op_sel:[1,0,0]
	v_pk_fma_f32 v[2:3], v[220:221], v[104:105], v[2:3] op_sel:[1,0,0]
	v_pk_fma_f32 v[4:5], v[220:221], v[106:107], v[4:5] op_sel:[1,0,0]
	ds_read_b128 v[210:213], v74 offset:4160
	ds_read_b128 v[214:217], v74 offset:4176
	ds_read_b128 v[218:221], v74 offset:4192
	s_waitcnt vmcnt(24) lgkmcnt(3)
	v_pk_fma_f32 v[46:47], v[222:223], v[108:109], v[46:47] op_sel_hi:[0,1,1]
	v_pk_fma_f32 v[48:49], v[222:223], v[110:111], v[48:49] op_sel_hi:[0,1,1]
	v_pk_fma_f32 v[34:35], v[226:227], v[108:109], v[34:35] op_sel_hi:[0,1,1]
	v_pk_fma_f32 v[36:37], v[226:227], v[110:111], v[36:37] op_sel_hi:[0,1,1]
	v_pk_fma_f32 v[14:15], v[230:231], v[108:109], v[14:15] op_sel_hi:[0,1,1]
	v_pk_fma_f32 v[16:17], v[230:231], v[110:111], v[16:17] op_sel_hi:[0,1,1]
	v_pk_fma_f32 v[42:43], v[222:223], v[108:109], v[42:43] op_sel:[1,0,0]
	v_pk_fma_f32 v[44:45], v[222:223], v[110:111], v[44:45] op_sel:[1,0,0]
	v_pk_fma_f32 v[26:27], v[226:227], v[108:109], v[26:27] op_sel:[1,0,0]
	v_pk_fma_f32 v[28:29], v[226:227], v[110:111], v[28:29] op_sel:[1,0,0]
	v_pk_fma_f32 v[10:11], v[230:231], v[108:109], v[10:11] op_sel:[1,0,0]
	v_pk_fma_f32 v[12:13], v[230:231], v[110:111], v[12:13] op_sel:[1,0,0]
	v_pk_fma_f32 v[38:39], v[224:225], v[108:109], v[38:39] op_sel_hi:[0,1,1]
	v_pk_fma_f32 v[40:41], v[224:225], v[110:111], v[40:41] op_sel_hi:[0,1,1]
	v_pk_fma_f32 v[22:23], v[228:229], v[108:109], v[22:23] op_sel_hi:[0,1,1]
	v_pk_fma_f32 v[24:25], v[228:229], v[110:111], v[24:25] op_sel_hi:[0,1,1]
	v_pk_fma_f32 v[6:7], v[232:233], v[108:109], v[6:7] op_sel_hi:[0,1,1]
	v_pk_fma_f32 v[8:9], v[232:233], v[110:111], v[8:9] op_sel_hi:[0,1,1]
	v_pk_fma_f32 v[30:31], v[224:225], v[108:109], v[30:31] op_sel:[1,0,0]
	v_pk_fma_f32 v[32:33], v[224:225], v[110:111], v[32:33] op_sel:[1,0,0]
	v_pk_fma_f32 v[18:19], v[228:229], v[108:109], v[18:19] op_sel:[1,0,0]
	v_pk_fma_f32 v[20:21], v[228:229], v[110:111], v[20:21] op_sel:[1,0,0]
	v_pk_fma_f32 v[2:3], v[232:233], v[108:109], v[2:3] op_sel:[1,0,0]
	v_pk_fma_f32 v[4:5], v[232:233], v[110:111], v[4:5] op_sel:[1,0,0]
	ds_read_b128 v[222:225], v74 offset:6240
	ds_read_b128 v[226:229], v74 offset:6256
	ds_read_b128 v[230:233], v74 offset:6272
	s_waitcnt vmcnt(23) lgkmcnt(3)
	v_pk_fma_f32 v[46:47], v[210:211], v[112:113], v[46:47] op_sel_hi:[0,1,1]
	v_pk_fma_f32 v[48:49], v[210:211], v[114:115], v[48:49] op_sel_hi:[0,1,1]
	v_pk_fma_f32 v[34:35], v[214:215], v[112:113], v[34:35] op_sel_hi:[0,1,1]
	v_pk_fma_f32 v[36:37], v[214:215], v[114:115], v[36:37] op_sel_hi:[0,1,1]
	v_pk_fma_f32 v[14:15], v[218:219], v[112:113], v[14:15] op_sel_hi:[0,1,1]
	v_pk_fma_f32 v[16:17], v[218:219], v[114:115], v[16:17] op_sel_hi:[0,1,1]
	v_pk_fma_f32 v[42:43], v[210:211], v[112:113], v[42:43] op_sel:[1,0,0]
	v_pk_fma_f32 v[44:45], v[210:211], v[114:115], v[44:45] op_sel:[1,0,0]
	v_pk_fma_f32 v[26:27], v[214:215], v[112:113], v[26:27] op_sel:[1,0,0]
	v_pk_fma_f32 v[28:29], v[214:215], v[114:115], v[28:29] op_sel:[1,0,0]
	v_pk_fma_f32 v[10:11], v[218:219], v[112:113], v[10:11] op_sel:[1,0,0]
	v_pk_fma_f32 v[12:13], v[218:219], v[114:115], v[12:13] op_sel:[1,0,0]
	v_pk_fma_f32 v[38:39], v[212:213], v[112:113], v[38:39] op_sel_hi:[0,1,1]
	v_pk_fma_f32 v[40:41], v[212:213], v[114:115], v[40:41] op_sel_hi:[0,1,1]
	v_pk_fma_f32 v[22:23], v[216:217], v[112:113], v[22:23] op_sel_hi:[0,1,1]
	v_pk_fma_f32 v[24:25], v[216:217], v[114:115], v[24:25] op_sel_hi:[0,1,1]
	v_pk_fma_f32 v[6:7], v[220:221], v[112:113], v[6:7] op_sel_hi:[0,1,1]
	v_pk_fma_f32 v[8:9], v[220:221], v[114:115], v[8:9] op_sel_hi:[0,1,1]
	v_pk_fma_f32 v[30:31], v[212:213], v[112:113], v[30:31] op_sel:[1,0,0]
	v_pk_fma_f32 v[32:33], v[212:213], v[114:115], v[32:33] op_sel:[1,0,0]
	v_pk_fma_f32 v[18:19], v[216:217], v[112:113], v[18:19] op_sel:[1,0,0]
	v_pk_fma_f32 v[20:21], v[216:217], v[114:115], v[20:21] op_sel:[1,0,0]
	v_pk_fma_f32 v[2:3], v[220:221], v[112:113], v[2:3] op_sel:[1,0,0]
	v_pk_fma_f32 v[4:5], v[220:221], v[114:115], v[4:5] op_sel:[1,0,0]
	ds_read_b128 v[210:213], v74 offset:8320
	ds_read_b128 v[214:217], v74 offset:8336
	ds_read_b128 v[218:221], v74 offset:8352
	s_waitcnt vmcnt(22) lgkmcnt(3)
; #define LAS __attribute__((address_space(3)))
; __device__ __forceinline__ void phase_prologue(const Frame& F) {
;     ...
;                 if (tid < 480) {
; #pragma unroll 2
;                     for (int kk = kl; kk < 256; kk += 10) {
;                         const f32x4 w4 = *(const f32x4*)(wada + (size_t)(kc * 256 + kk) * MODW + 48 * cb + 4 * cgp);
;                         const f32x2 w01 = (f32x2){w4[0], w4[1]}, w23 = (f32x2){w4[2], w4[3]};
;                         const LAS f32x4* sp = (const LAS f32x4*)(sT + kk * 52 + 12 * cdg);
;                         const f32x4 s0 = sp[0], s1 = sp[1], s2 = sp[2];
; #pragma unroll
;                         for (int c = 0; c < 4; ++c) {
;                             acc[c][0] = __builtin_elementwise_fma((f32x2){s0[c], s0[c]}, w01, acc[c][0]); acc[c][1] = __builtin_elementwise_fma((f32x2){s0[c], s0[c]}, w23, acc[c][1]);
;                             acc[4 + c][0] = __builtin_elementwise_fma((f32x2){s1[c], s1[c]}, w01, acc[4 + c][0]); acc[4 + c][1] = __builtin_elementwise_fma((f32x2){s1[c], s1[c]}, w23, acc[4 + c][1]);
;                             acc[8 + c][0] = __builtin_elementwise_fma((f32x2){s2[c], s2[c]}, w01, acc[8 + c][0]); acc[8 + c][1] = __builtin_elementwise_fma((f32x2){s2[c], s2[c]}, w23, acc[8 + c][1]); }
;                     }
	v_pk_fma_f32 v[46:47], v[222:223], v[116:117], v[46:47] op_sel_hi:[0,1,1]
	v_pk_fma_f32 v[48:49], v[222:223], v[118:119], v[48:49] op_sel_hi:[0,1,1]
	v_pk_fma_f32 v[34:35], v[226:227], v[116:117], v[34:35] op_sel_hi:[0,1,1]
	v_pk_fma_f32 v[36:37], v[226:227], v[118:119], v[36:37] op_sel_hi:[0,1,1]
	v_pk_fma_f32 v[14:15], v[230:231], v[116:117], v[14:15] op_sel_hi:[0,1,1]
	v_pk_fma_f32 v[16:17], v[230:231], v[118:119], v[16:17] op_sel_hi:[0,1,1]
	v_pk_fma_f32 v[42:43], v[222:223], v[116:117], v[42:43] op_sel:[1,0,0]
	v_pk_fma_f32 v[44:45], v[222:223], v[118:119], v[44:45] op_sel:[1,0,0]
	v_pk_fma_f32 v[26:27], v[226:227], v[116:117], v[26:27] op_sel:[1,0,0]
	v_pk_fma_f32 v[28:29], v[226:227], v[118:119], v[28:29] op_sel:[1,0,0]
	v_pk_fma_f32 v[10:11], v[230:231], v[116:117], v[10:11] op_sel:[1,0,0]
	v_pk_fma_f32 v[12:13], v[230:231], v[118:119], v[12:13] op_sel:[1,0,0]
	v_pk_fma_f32 v[38:39], v[224:225], v[116:117], v[38:39] op_sel_hi:[0,1,1]
	v_pk_fma_f32 v[40:41], v[224:225], v[118:119], v[40:41] op_sel_hi:[0,1,1]
	v_pk_fma_f32 v[22:23], v[228:229], v[116:117], v[22:23] op_sel_hi:[0,1,1]
	v_pk_fma_f32 v[24:25], v[228:229], v[118:119], v[24:25] op_sel_hi:[0,1,1]
	v_pk_fma_f32 v[6:7], v[232:233], v[116:117], v[6:7] op_sel_hi:[0,1,1]
	v_pk_fma_f32 v[8:9], v[232:233], v[118:119], v[8:9] op_sel_hi:[0,1,1]
	v_pk_fma_f32 v[30:31], v[224:225], v[116:117], v[30:31] op_sel:[1,0,0]
	v_pk_fma_f32 v[32:33], v[224:225], v[118:119], v[32:33] op_sel:[1,0,0]
	v_pk_fma_f32 v[18:19], v[228:229], v[116:117], v[18:19] op_sel:[1,0,0]
	v_pk_fma_f32 v[20:21], v[228:229], v[118:119], v[20:21] op_sel:[1,0,0]
	v_pk_fma_f32 v[2:3], v[232:233], v[116:117], v[2:3] op_sel:[1,0,0]
	v_pk_fma_f32 v[4:5], v[232:233], v[118:119], v[4:5] op_sel:[1,0,0]
	ds_read_b128 v[222:225], v74 offset:10400
	ds_read_b128 v[226:229], v74 offset:10416
	ds_read_b128 v[230:233], v74 offset:10432
	s_waitcnt vmcnt(21) lgkmcnt(3)
	v_pk_fma_f32 v[46:47], v[210:211], v[120:121], v[46:47] op_sel_hi:[0,1,1]
	v_pk_fma_f32 v[48:49], v[210:211], v[122:123], v[48:49] op_sel_hi:[0,1,1]
	v_pk_fma_f32 v[34:35], v[214:215], v[120:121], v[34:35] op_sel_hi:[0,1,1]
	v_pk_fma_f32 v[36:37], v[214:215], v[122:123], v[36:37] op_sel_hi:[0,1,1]
	v_pk_fma_f32 v[14:15], v[218:219], v[120:121], v[14:15] op_sel_hi:[0,1,1]
	v_pk_fma_f32 v[16:17], v[218:219], v[122:123], v[16:17] op_sel_hi:[0,1,1]
	v_pk_fma_f32 v[42:43], v[210:211], v[120:121], v[42:43] op_sel:[1,0,0]
	v_pk_fma_f32 v[44:45], v[210:211], v[122:123], v[44:45] op_sel:[1,0,0]
	v_pk_fma_f32 v[26:27], v[214:215], v[120:121], v[26:27] op_sel:[1,0,0]
	v_pk_fma_f32 v[28:29], v[214:215], v[122:123], v[28:29] op_sel:[1,0,0]
	v_pk_fma_f32 v[10:11], v[218:219], v[120:121], v[10:11] op_sel:[1,0,0]
	v_pk_fma_f32 v[12:13], v[218:219], v[122:123], v[12:13] op_sel:[1,0,0]
	v_pk_fma_f32 v[38:39], v[212:213], v[120:121], v[38:39] op_sel_hi:[0,1,1]
	v_pk_fma_f32 v[40:41], v[212:213], v[122:123], v[40:41] op_sel_hi:[0,1,1]
	v_pk_fma_f32 v[22:23], v[216:217], v[120:121], v[22:23] op_sel_hi:[0,1,1]
	v_pk_fma_f32 v[24:25], v[216:217], v[122:123], v[24:25] op_sel_hi:[0,1,1]
	v_pk_fma_f32 v[6:7], v[220:221], v[120:121], v[6:7] op_sel_hi:[0,1,1]
	v_pk_fma_f32 v[8:9], v[220:221], v[122:123], v[8:9] op_sel_hi:[0,1,1]
	v_pk_fma_f32 v[30:31], v[212:213], v[120:121], v[30:31] op_sel:[1,0,0]
	v_pk_fma_f32 v[32:33], v[212:213], v[122:123], v[32:33] op_sel:[1,0,0]
	v_pk_fma_f32 v[18:19], v[216:217], v[120:121], v[18:19] op_sel:[1,0,0]
	v_pk_fma_f32 v[20:21], v[216:217], v[122:123], v[20:21] op_sel:[1,0,0]
	v_pk_fma_f32 v[2:3], v[220:221], v[120:121], v[2:3] op_sel:[1,0,0]
	v_pk_fma_f32 v[4:5], v[220:221], v[122:123], v[4:5] op_sel:[1,0,0]
	ds_read_b128 v[210:213], v74 offset:12480
	ds_read_b128 v[214:217], v74 offset:12496
	ds_read_b128 v[218:221], v74 offset:12512
	s_waitcnt vmcnt(20) lgkmcnt(3)
	v_pk_fma_f32 v[46:47], v[222:223], v[124:125], v[46:47] op_sel_hi:[0,1,1]
	v_pk_fma_f32 v[48:49], v[222:223], v[126:127], v[48:49] op_sel_hi:[0,1,1]
	v_pk_fma_f32 v[34:35], v[226:227], v[124:125], v[34:35] op_sel_hi:[0,1,1]
	v_pk_fma_f32 v[36:37], v[226:227], v[126:127], v[36:37] op_sel_hi:[0,1,1]
	v_pk_fma_f32 v[14:15], v[230:231], v[124:125], v[14:15] op_sel_hi:[0,1,1]
	v_pk_fma_f32 v[16:17], v[230:231], v[126:127], v[16:17] op_sel_hi:[0,1,1]
	v_pk_fma_f32 v[42:43], v[222:223], v[124:125], v[42:43] op_sel:[1,0,0]
	v_pk_fma_f32 v[44:45], v[222:223], v[126:127], v[44:45] op_sel:[1,0,0]
	v_pk_fma_f32 v[26:27], v[226:227], v[124:125], v[26:27] op_sel:[1,0,0]
	v_pk_fma_f32 v[28:29], v[226:227], v[126:127], v[28:29] op_sel:[1,0,0]
	v_pk_fma_f32 v[10:11], v[230:231], v[124:125], v[10:11] op_sel:[1,0,0]
	v_pk_fma_f32 v[12:13], v[230:231], v[126:127], v[12:13] op_sel:[1,0,0]
	v_pk_fma_f32 v[38:39], v[224:225], v[124:125], v[38:39] op_sel_hi:[0,1,1]
	v_pk_fma_f32 v[40:41], v[224:225], v[126:127], v[40:41] op_sel_hi:[0,1,1]
	v_pk_fma_f32 v[22:23], v[228:229], v[124:125], v[22:23] op_sel_hi:[0,1,1]
	v_pk_fma_f32 v[24:25], v[228:229], v[126:127], v[24:25] op_sel_hi:[0,1,1]
	v_pk_fma_f32 v[6:7], v[232:233], v[124:125], v[6:7] op_sel_hi:[0,1,1]
	v_pk_fma_f32 v[8:9], v[232:233], v[126:127], v[8:9] op_sel_hi:[0,1,1]
	v_pk_fma_f32 v[30:31], v[224:225], v[124:125], v[30:31] op_sel:[1,0,0]
	v_pk_fma_f32 v[32:33], v[224:225], v[126:127], v[32:33] op_sel:[1,0,0]
	v_pk_fma_f32 v[18:19], v[228:229], v[124:125], v[18:19] op_sel:[1,0,0]
	v_pk_fma_f32 v[20:21], v[228:229], v[126:127], v[20:21] op_sel:[1,0,0]
	v_pk_fma_f32 v[2:3], v[232:233], v[124:125], v[2:3] op_sel:[1,0,0]
	v_pk_fma_f32 v[4:5], v[232:233], v[126:127], v[4:5] op_sel:[1,0,0]
	ds_read_b128 v[222:225], v74 offset:14560
	ds_read_b128 v[226:229], v74 offset:14576
	ds_read_b128 v[230:233], v74 offset:14592
	s_waitcnt vmcnt(19) lgkmcnt(3)
; #define LAS __attribute__((address_space(3)))
; __device__ __forceinline__ void phase_prologue(const Frame& F) {
;     ...
;                 if (tid < 480) {
; #pragma unroll 2
;                     for (int kk = kl; kk < 256; kk += 10) {
;                         const f32x4 w4 = *(const f32x4*)(wada + (size_t)(kc * 256 + kk) * MODW + 48 * cb + 4 * cgp);
;                         const f32x2 w01 = (f32x2){w4[0], w4[1]}, w23 = (f32x2){w4[2], w4[3]};
;                         const LAS f32x4* sp = (const LAS f32x4*)(sT + kk * 52 + 12 * cdg);
;                         const f32x4 s0 = sp[0], s1 = sp[1], s2 = sp[2];
; #pragma unroll
;                         for (int c = 0; c < 4; ++c) {
;                             acc[c][0] = __builtin_elementwise_fma((f32x2){s0[c], s0[c]}, w01, acc[c][0]); acc[c][1] = __builtin_elementwise_fma((f32x2){s0[c], s0[c]}, w23, acc[c][1]);
;                             acc[4 + c][0] = __builtin_elementwise_fma((f32x2){s1[c], s1[c]}, w01, acc[4 + c][0]); acc[4 + c][1] = __builtin_elementwise_fma((f32x2){s1[c], s1[c]}, w23, acc[4 + c][1]);
;                             acc[8 + c][0] = __builtin_elementwise_fma((f32x2){s2[c], s2[c]}, w01, acc[8 + c][0]); acc[8 + c][1] = __builtin_elementwise_fma((f32x2){s2[c], s2[c]}, w23, acc[8 + c][1]); }
;                     }
	v_pk_fma_f32 v[46:47], v[210:211], v[128:129], v[46:47] op_sel_hi:[0,1,1]
	v_pk_fma_f32 v[48:49], v[210:211], v[130:131], v[48:49] op_sel_hi:[0,1,1]
	v_pk_fma_f32 v[34:35], v[214:215], v[128:129], v[34:35] op_sel_hi:[0,1,1]
	v_pk_fma_f32 v[36:37], v[214:215], v[130:131], v[36:37] op_sel_hi:[0,1,1]
	v_pk_fma_f32 v[14:15], v[218:219], v[128:129], v[14:15] op_sel_hi:[0,1,1]
	v_pk_fma_f32 v[16:17], v[218:219], v[130:131], v[16:17] op_sel_hi:[0,1,1]
	v_pk_fma_f32 v[42:43], v[210:211], v[128:129], v[42:43] op_sel:[1,0,0]
	v_pk_fma_f32 v[44:45], v[210:211], v[130:131], v[44:45] op_sel:[1,0,0]
	v_pk_fma_f32 v[26:27], v[214:215], v[128:129], v[26:27] op_sel:[1,0,0]
	v_pk_fma_f32 v[28:29], v[214:215], v[130:131], v[28:29] op_sel:[1,0,0]
	v_pk_fma_f32 v[10:11], v[218:219], v[128:129], v[10:11] op_sel:[1,0,0]
	v_pk_fma_f32 v[12:13], v[218:219], v[130:131], v[12:13] op_sel:[1,0,0]
	v_pk_fma_f32 v[38:39], v[212:213], v[128:129], v[38:39] op_sel_hi:[0,1,1]
	v_pk_fma_f32 v[40:41], v[212:213], v[130:131], v[40:41] op_sel_hi:[0,1,1]
	v_pk_fma_f32 v[22:23], v[216:217], v[128:129], v[22:23] op_sel_hi:[0,1,1]
	v_pk_fma_f32 v[24:25], v[216:217], v[130:131], v[24:25] op_sel_hi:[0,1,1]
	v_pk_fma_f32 v[6:7], v[220:221], v[128:129], v[6:7] op_sel_hi:[0,1,1]
	v_pk_fma_f32 v[8:9], v[220:221], v[130:131], v[8:9] op_sel_hi:[0,1,1]
	v_pk_fma_f32 v[30:31], v[212:213], v[128:129], v[30:31] op_sel:[1,0,0]
	v_pk_fma_f32 v[32:33], v[212:213], v[130:131], v[32:33] op_sel:[1,0,0]
	v_pk_fma_f32 v[18:19], v[216:217], v[128:129], v[18:19] op_sel:[1,0,0]
	v_pk_fma_f32 v[20:21], v[216:217], v[130:131], v[20:21] op_sel:[1,0,0]
	v_pk_fma_f32 v[2:3], v[220:221], v[128:129], v[2:3] op_sel:[1,0,0]
	v_pk_fma_f32 v[4:5], v[220:221], v[130:131], v[4:5] op_sel:[1,0,0]
	ds_read_b128 v[210:213], v74 offset:16640
	ds_read_b128 v[214:217], v74 offset:16656
	ds_read_b128 v[218:221], v74 offset:16672
	s_waitcnt vmcnt(18) lgkmcnt(3)
	v_pk_fma_f32 v[46:47], v[222:223], v[132:133], v[46:47] op_sel_hi:[0,1,1]
	v_pk_fma_f32 v[48:49], v[222:223], v[134:135], v[48:49] op_sel_hi:[0,1,1]
	v_pk_fma_f32 v[34:35], v[226:227], v[132:133], v[34:35] op_sel_hi:[0,1,1]
	v_pk_fma_f32 v[36:37], v[226:227], v[134:135], v[36:37] op_sel_hi:[0,1,1]
	v_pk_fma_f32 v[14:15], v[230:231], v[132:133], v[14:15] op_sel_hi:[0,1,1]
	v_pk_fma_f32 v[16:17], v[230:231], v[134:135], v[16:17] op_sel_hi:[0,1,1]
	v_pk_fma_f32 v[42:43], v[222:223], v[132:133], v[42:43] op_sel:[1,0,0]
	v_pk_fma_f32 v[44:45], v[222:223], v[134:135], v[44:45] op_sel:[1,0,0]
	v_pk_fma_f32 v[26:27], v[226:227], v[132:133], v[26:27] op_sel:[1,0,0]
	v_pk_fma_f32 v[28:29], v[226:227], v[134:135], v[28:29] op_sel:[1,0,0]
	v_pk_fma_f32 v[10:11], v[230:231], v[132:133], v[10:11] op_sel:[1,0,0]
	v_pk_fma_f32 v[12:13], v[230:231], v[134:135], v[12:13] op_sel:[1,0,0]
	v_pk_fma_f32 v[38:39], v[224:225], v[132:133], v[38:39] op_sel_hi:[0,1,1]
	v_pk_fma_f32 v[40:41], v[224:225], v[134:135], v[40:41] op_sel_hi:[0,1,1]
	v_pk_fma_f32 v[22:23], v[228:229], v[132:133], v[22:23] op_sel_hi:[0,1,1]
	v_pk_fma_f32 v[24:25], v[228:229], v[134:135], v[24:25] op_sel_hi:[0,1,1]
	v_pk_fma_f32 v[6:7], v[232:233], v[132:133], v[6:7] op_sel_hi:[0,1,1]
	v_pk_fma_f32 v[8:9], v[232:233], v[134:135], v[8:9] op_sel_hi:[0,1,1]
	v_pk_fma_f32 v[30:31], v[224:225], v[132:133], v[30:31] op_sel:[1,0,0]
	v_pk_fma_f32 v[32:33], v[224:225], v[134:135], v[32:33] op_sel:[1,0,0]
	v_pk_fma_f32 v[18:19], v[228:229], v[132:133], v[18:19] op_sel:[1,0,0]
	v_pk_fma_f32 v[20:21], v[228:229], v[134:135], v[20:21] op_sel:[1,0,0]
	v_pk_fma_f32 v[2:3], v[232:233], v[132:133], v[2:3] op_sel:[1,0,0]
	v_pk_fma_f32 v[4:5], v[232:233], v[134:135], v[4:5] op_sel:[1,0,0]
	ds_read_b128 v[222:225], v74 offset:18720
	ds_read_b128 v[226:229], v74 offset:18736
	ds_read_b128 v[230:233], v74 offset:18752
	s_waitcnt vmcnt(17) lgkmcnt(3)
	v_pk_fma_f32 v[46:47], v[210:211], v[136:137], v[46:47] op_sel_hi:[0,1,1]
	v_pk_fma_f32 v[48:49], v[210:211], v[138:139], v[48:49] op_sel_hi:[0,1,1]
	v_pk_fma_f32 v[34:35], v[214:215], v[136:137], v[34:35] op_sel_hi:[0,1,1]
	v_pk_fma_f32 v[36:37], v[214:215], v[138:139], v[36:37] op_sel_hi:[0,1,1]
	v_pk_fma_f32 v[14:15], v[218:219], v[136:137], v[14:15] op_sel_hi:[0,1,1]
	v_pk_fma_f32 v[16:17], v[218:219], v[138:139], v[16:17] op_sel_hi:[0,1,1]
	v_pk_fma_f32 v[42:43], v[210:211], v[136:137], v[42:43] op_sel:[1,0,0]
	v_pk_fma_f32 v[44:45], v[210:211], v[138:139], v[44:45] op_sel:[1,0,0]
	v_pk_fma_f32 v[26:27], v[214:215], v[136:137], v[26:27] op_sel:[1,0,0]
	v_pk_fma_f32 v[28:29], v[214:215], v[138:139], v[28:29] op_sel:[1,0,0]
	v_pk_fma_f32 v[10:11], v[218:219], v[136:137], v[10:11] op_sel:[1,0,0]
	v_pk_fma_f32 v[12:13], v[218:219], v[138:139], v[12:13] op_sel:[1,0,0]
	v_pk_fma_f32 v[38:39], v[212:213], v[136:137], v[38:39] op_sel_hi:[0,1,1]
	v_pk_fma_f32 v[40:41], v[212:213], v[138:139], v[40:41] op_sel_hi:[0,1,1]
	v_pk_fma_f32 v[22:23], v[216:217], v[136:137], v[22:23] op_sel_hi:[0,1,1]
	v_pk_fma_f32 v[24:25], v[216:217], v[138:139], v[24:25] op_sel_hi:[0,1,1]
	v_pk_fma_f32 v[6:7], v[220:221], v[136:137], v[6:7] op_sel_hi:[0,1,1]
	v_pk_fma_f32 v[8:9], v[220:221], v[138:139], v[8:9] op_sel_hi:[0,1,1]
	v_pk_fma_f32 v[30:31], v[212:213], v[136:137], v[30:31] op_sel:[1,0,0]
	v_pk_fma_f32 v[32:33], v[212:213], v[138:139], v[32:33] op_sel:[1,0,0]
	v_pk_fma_f32 v[18:19], v[216:217], v[136:137], v[18:19] op_sel:[1,0,0]
	v_pk_fma_f32 v[20:21], v[216:217], v[138:139], v[20:21] op_sel:[1,0,0]
	v_pk_fma_f32 v[2:3], v[220:221], v[136:137], v[2:3] op_sel:[1,0,0]
	v_pk_fma_f32 v[4:5], v[220:221], v[138:139], v[4:5] op_sel:[1,0,0]
	ds_read_b128 v[210:213], v74 offset:20800
	ds_read_b128 v[214:217], v74 offset:20816
	ds_read_b128 v[218:221], v74 offset:20832
	s_waitcnt vmcnt(16) lgkmcnt(3)
; #define LAS __attribute__((address_space(3)))
; __device__ __forceinline__ void phase_prologue(const Frame& F) {
;     ...
;                 if (tid < 480) {
; #pragma unroll 2
;                     for (int kk = kl; kk < 256; kk += 10) {
;                         const f32x4 w4 = *(const f32x4*)(wada + (size_t)(kc * 256 + kk) * MODW + 48 * cb + 4 * cgp);
;                         const f32x2 w01 = (f32x2){w4[0], w4[1]}, w23 = (f32x2){w4[2], w4[3]};
;                         const LAS f32x4* sp = (const LAS f32x4*)(sT + kk * 52 + 12 * cdg);
;                         const f32x4 s0 = sp[0], s1 = sp[1], s2 = sp[2];
; #pragma unroll
;                         for (int c = 0; c < 4; ++c) {
;                             acc[c][0] = __builtin_elementwise_fma((f32x2){s0[c], s0[c]}, w01, acc[c][0]); acc[c][1] = __builtin_elementwise_fma((f32x2){s0[c], s0[c]}, w23, acc[c][1]);
;                             acc[4 + c][0] = __builtin_elementwise_fma((f32x2){s1[c], s1[c]}, w01, acc[4 + c][0]); acc[4 + c][1] = __builtin_elementwise_fma((f32x2){s1[c], s1[c]}, w23, acc[4 + c][1]);
;                             acc[8 + c][0] = __builtin_elementwise_fma((f32x2){s2[c], s2[c]}, w01, acc[8 + c][0]); acc[8 + c][1] = __builtin_elementwise_fma((f32x2){s2[c], s2[c]}, w23, acc[8 + c][1]); }
;                     }
	v_pk_fma_f32 v[46:47], v[222:223], v[140:141], v[46:47] op_sel_hi:[0,1,1]
	v_pk_fma_f32 v[48:49], v[222:223], v[142:143], v[48:49] op_sel_hi:[0,1,1]
	v_pk_fma_f32 v[34:35], v[226:227], v[140:141], v[34:35] op_sel_hi:[0,1,1]
	v_pk_fma_f32 v[36:37], v[226:227], v[142:143], v[36:37] op_sel_hi:[0,1,1]
	v_pk_fma_f32 v[14:15], v[230:231], v[140:141], v[14:15] op_sel_hi:[0,1,1]
	v_pk_fma_f32 v[16:17], v[230:231], v[142:143], v[16:17] op_sel_hi:[0,1,1]
	v_pk_fma_f32 v[42:43], v[222:223], v[140:141], v[42:43] op_sel:[1,0,0]
	v_pk_fma_f32 v[44:45], v[222:223], v[142:143], v[44:45] op_sel:[1,0,0]
	v_pk_fma_f32 v[26:27], v[226:227], v[140:141], v[26:27] op_sel:[1,0,0]
	v_pk_fma_f32 v[28:29], v[226:227], v[142:143], v[28:29] op_sel:[1,0,0]
	v_pk_fma_f32 v[10:11], v[230:231], v[140:141], v[10:11] op_sel:[1,0,0]
	v_pk_fma_f32 v[12:13], v[230:231], v[142:143], v[12:13] op_sel:[1,0,0]
	v_pk_fma_f32 v[38:39], v[224:225], v[140:141], v[38:39] op_sel_hi:[0,1,1]
	v_pk_fma_f32 v[40:41], v[224:225], v[142:143], v[40:41] op_sel_hi:[0,1,1]
	v_pk_fma_f32 v[22:23], v[228:229], v[140:141], v[22:23] op_sel_hi:[0,1,1]
	v_pk_fma_f32 v[24:25], v[228:229], v[142:143], v[24:25] op_sel_hi:[0,1,1]
	v_pk_fma_f32 v[6:7], v[232:233], v[140:141], v[6:7] op_sel_hi:[0,1,1]
	v_pk_fma_f32 v[8:9], v[232:233], v[142:143], v[8:9] op_sel_hi:[0,1,1]
	v_pk_fma_f32 v[30:31], v[224:225], v[140:141], v[30:31] op_sel:[1,0,0]
	v_pk_fma_f32 v[32:33], v[224:225], v[142:143], v[32:33] op_sel:[1,0,0]
	v_pk_fma_f32 v[18:19], v[228:229], v[140:141], v[18:19] op_sel:[1,0,0]
	v_pk_fma_f32 v[20:21], v[228:229], v[142:143], v[20:21] op_sel:[1,0,0]
	v_pk_fma_f32 v[2:3], v[232:233], v[140:141], v[2:3] op_sel:[1,0,0]
	v_pk_fma_f32 v[4:5], v[232:233], v[142:143], v[4:5] op_sel:[1,0,0]
	ds_read_b128 v[222:225], v74 offset:22880
	ds_read_b128 v[226:229], v74 offset:22896
	ds_read_b128 v[230:233], v74 offset:22912
	s_waitcnt vmcnt(15) lgkmcnt(3)
	v_pk_fma_f32 v[46:47], v[210:211], v[144:145], v[46:47] op_sel_hi:[0,1,1]
	v_pk_fma_f32 v[48:49], v[210:211], v[146:147], v[48:49] op_sel_hi:[0,1,1]
	v_pk_fma_f32 v[34:35], v[214:215], v[144:145], v[34:35] op_sel_hi:[0,1,1]
	v_pk_fma_f32 v[36:37], v[214:215], v[146:147], v[36:37] op_sel_hi:[0,1,1]
	v_pk_fma_f32 v[14:15], v[218:219], v[144:145], v[14:15] op_sel_hi:[0,1,1]
	v_pk_fma_f32 v[16:17], v[218:219], v[146:147], v[16:17] op_sel_hi:[0,1,1]
	v_pk_fma_f32 v[42:43], v[210:211], v[144:145], v[42:43] op_sel:[1,0,0]
	v_pk_fma_f32 v[44:45], v[210:211], v[146:147], v[44:45] op_sel:[1,0,0]
	v_pk_fma_f32 v[26:27], v[214:215], v[144:145], v[26:27] op_sel:[1,0,0]
	v_pk_fma_f32 v[28:29], v[214:215], v[146:147], v[28:29] op_sel:[1,0,0]
	v_pk_fma_f32 v[10:11], v[218:219], v[144:145], v[10:11] op_sel:[1,0,0]
	v_pk_fma_f32 v[12:13], v[218:219], v[146:147], v[12:13] op_sel:[1,0,0]
	v_pk_fma_f32 v[38:39], v[212:213], v[144:145], v[38:39] op_sel_hi:[0,1,1]
	v_pk_fma_f32 v[40:41], v[212:213], v[146:147], v[40:41] op_sel_hi:[0,1,1]
	v_pk_fma_f32 v[22:23], v[216:217], v[144:145], v[22:23] op_sel_hi:[0,1,1]
	v_pk_fma_f32 v[24:25], v[216:217], v[146:147], v[24:25] op_sel_hi:[0,1,1]
	v_pk_fma_f32 v[6:7], v[220:221], v[144:145], v[6:7] op_sel_hi:[0,1,1]
	v_pk_fma_f32 v[8:9], v[220:221], v[146:147], v[8:9] op_sel_hi:[0,1,1]
	v_pk_fma_f32 v[30:31], v[212:213], v[144:145], v[30:31] op_sel:[1,0,0]
	v_pk_fma_f32 v[32:33], v[212:213], v[146:147], v[32:33] op_sel:[1,0,0]
	v_pk_fma_f32 v[18:19], v[216:217], v[144:145], v[18:19] op_sel:[1,0,0]
	v_pk_fma_f32 v[20:21], v[216:217], v[146:147], v[20:21] op_sel:[1,0,0]
	v_pk_fma_f32 v[2:3], v[220:221], v[144:145], v[2:3] op_sel:[1,0,0]
	v_pk_fma_f32 v[4:5], v[220:221], v[146:147], v[4:5] op_sel:[1,0,0]
	ds_read_b128 v[210:213], v74 offset:24960
	ds_read_b128 v[214:217], v74 offset:24976
	ds_read_b128 v[218:221], v74 offset:24992
	s_waitcnt vmcnt(14) lgkmcnt(3)
	v_pk_fma_f32 v[46:47], v[222:223], v[148:149], v[46:47] op_sel_hi:[0,1,1]
	v_pk_fma_f32 v[48:49], v[222:223], v[150:151], v[48:49] op_sel_hi:[0,1,1]
	v_pk_fma_f32 v[34:35], v[226:227], v[148:149], v[34:35] op_sel_hi:[0,1,1]
	v_pk_fma_f32 v[36:37], v[226:227], v[150:151], v[36:37] op_sel_hi:[0,1,1]
	v_pk_fma_f32 v[14:15], v[230:231], v[148:149], v[14:15] op_sel_hi:[0,1,1]
	v_pk_fma_f32 v[16:17], v[230:231], v[150:151], v[16:17] op_sel_hi:[0,1,1]
	v_pk_fma_f32 v[42:43], v[222:223], v[148:149], v[42:43] op_sel:[1,0,0]
	v_pk_fma_f32 v[44:45], v[222:223], v[150:151], v[44:45] op_sel:[1,0,0]
	v_pk_fma_f32 v[26:27], v[226:227], v[148:149], v[26:27] op_sel:[1,0,0]
	v_pk_fma_f32 v[28:29], v[226:227], v[150:151], v[28:29] op_sel:[1,0,0]
	v_pk_fma_f32 v[10:11], v[230:231], v[148:149], v[10:11] op_sel:[1,0,0]
	v_pk_fma_f32 v[12:13], v[230:231], v[150:151], v[12:13] op_sel:[1,0,0]
	v_pk_fma_f32 v[38:39], v[224:225], v[148:149], v[38:39] op_sel_hi:[0,1,1]
	v_pk_fma_f32 v[40:41], v[224:225], v[150:151], v[40:41] op_sel_hi:[0,1,1]
	v_pk_fma_f32 v[22:23], v[228:229], v[148:149], v[22:23] op_sel_hi:[0,1,1]
	v_pk_fma_f32 v[24:25], v[228:229], v[150:151], v[24:25] op_sel_hi:[0,1,1]
	v_pk_fma_f32 v[6:7], v[232:233], v[148:149], v[6:7] op_sel_hi:[0,1,1]
	v_pk_fma_f32 v[8:9], v[232:233], v[150:151], v[8:9] op_sel_hi:[0,1,1]
	v_pk_fma_f32 v[30:31], v[224:225], v[148:149], v[30:31] op_sel:[1,0,0]
	v_pk_fma_f32 v[32:33], v[224:225], v[150:151], v[32:33] op_sel:[1,0,0]
	v_pk_fma_f32 v[18:19], v[228:229], v[148:149], v[18:19] op_sel:[1,0,0]
	v_pk_fma_f32 v[20:21], v[228:229], v[150:151], v[20:21] op_sel:[1,0,0]
	v_pk_fma_f32 v[2:3], v[232:233], v[148:149], v[2:3] op_sel:[1,0,0]
	v_pk_fma_f32 v[4:5], v[232:233], v[150:151], v[4:5] op_sel:[1,0,0]
	ds_read_b128 v[222:225], v74 offset:27040
	ds_read_b128 v[226:229], v74 offset:27056
	ds_read_b128 v[230:233], v74 offset:27072
	s_waitcnt vmcnt(13) lgkmcnt(3)
; #define LAS __attribute__((address_space(3)))
; __device__ __forceinline__ void phase_prologue(const Frame& F) {
;     ...
;                 if (tid < 480) {
; #pragma unroll 2
;                     for (int kk = kl; kk < 256; kk += 10) {
;                         const f32x4 w4 = *(const f32x4*)(wada + (size_t)(kc * 256 + kk) * MODW + 48 * cb + 4 * cgp);
;                         const f32x2 w01 = (f32x2){w4[0], w4[1]}, w23 = (f32x2){w4[2], w4[3]};
;                         const LAS f32x4* sp = (const LAS f32x4*)(sT + kk * 52 + 12 * cdg);
;                         const f32x4 s0 = sp[0], s1 = sp[1], s2 = sp[2];
; #pragma unroll
;                         for (int c = 0; c < 4; ++c) {
;                             acc[c][0] = __builtin_elementwise_fma((f32x2){s0[c], s0[c]}, w01, acc[c][0]); acc[c][1] = __builtin_elementwise_fma((f32x2){s0[c], s0[c]}, w23, acc[c][1]);
;                             acc[4 + c][0] = __builtin_elementwise_fma((f32x2){s1[c], s1[c]}, w01, acc[4 + c][0]); acc[4 + c][1] = __builtin_elementwise_fma((f32x2){s1[c], s1[c]}, w23, acc[4 + c][1]);
;                             acc[8 + c][0] = __builtin_elementwise_fma((f32x2){s2[c], s2[c]}, w01, acc[8 + c][0]); acc[8 + c][1] = __builtin_elementwise_fma((f32x2){s2[c], s2[c]}, w23, acc[8 + c][1]); }
;                     }
	v_pk_fma_f32 v[46:47], v[210:211], v[152:153], v[46:47] op_sel_hi:[0,1,1]
	v_pk_fma_f32 v[48:49], v[210:211], v[154:155], v[48:49] op_sel_hi:[0,1,1]
	v_pk_fma_f32 v[34:35], v[214:215], v[152:153], v[34:35] op_sel_hi:[0,1,1]
	v_pk_fma_f32 v[36:37], v[214:215], v[154:155], v[36:37] op_sel_hi:[0,1,1]
	v_pk_fma_f32 v[14:15], v[218:219], v[152:153], v[14:15] op_sel_hi:[0,1,1]
	v_pk_fma_f32 v[16:17], v[218:219], v[154:155], v[16:17] op_sel_hi:[0,1,1]
	v_pk_fma_f32 v[42:43], v[210:211], v[152:153], v[42:43] op_sel:[1,0,0]
	v_pk_fma_f32 v[44:45], v[210:211], v[154:155], v[44:45] op_sel:[1,0,0]
	v_pk_fma_f32 v[26:27], v[214:215], v[152:153], v[26:27] op_sel:[1,0,0]
	v_pk_fma_f32 v[28:29], v[214:215], v[154:155], v[28:29] op_sel:[1,0,0]
	v_pk_fma_f32 v[10:11], v[218:219], v[152:153], v[10:11] op_sel:[1,0,0]
	v_pk_fma_f32 v[12:13], v[218:219], v[154:155], v[12:13] op_sel:[1,0,0]
	v_pk_fma_f32 v[38:39], v[212:213], v[152:153], v[38:39] op_sel_hi:[0,1,1]
	v_pk_fma_f32 v[40:41], v[212:213], v[154:155], v[40:41] op_sel_hi:[0,1,1]
	v_pk_fma_f32 v[22:23], v[216:217], v[152:153], v[22:23] op_sel_hi:[0,1,1]
	v_pk_fma_f32 v[24:25], v[216:217], v[154:155], v[24:25] op_sel_hi:[0,1,1]
	v_pk_fma_f32 v[6:7], v[220:221], v[152:153], v[6:7] op_sel_hi:[0,1,1]
	v_pk_fma_f32 v[8:9], v[220:221], v[154:155], v[8:9] op_sel_hi:[0,1,1]
	v_pk_fma_f32 v[30:31], v[212:213], v[152:153], v[30:31] op_sel:[1,0,0]
	v_pk_fma_f32 v[32:33], v[212:213], v[154:155], v[32:33] op_sel:[1,0,0]
	v_pk_fma_f32 v[18:19], v[216:217], v[152:153], v[18:19] op_sel:[1,0,0]
	v_pk_fma_f32 v[20:21], v[216:217], v[154:155], v[20:21] op_sel:[1,0,0]
	v_pk_fma_f32 v[2:3], v[220:221], v[152:153], v[2:3] op_sel:[1,0,0]
	v_pk_fma_f32 v[4:5], v[220:221], v[154:155], v[4:5] op_sel:[1,0,0]
	ds_read_b128 v[210:213], v74 offset:29120
	ds_read_b128 v[214:217], v74 offset:29136
	ds_read_b128 v[218:221], v74 offset:29152
	s_waitcnt vmcnt(12) lgkmcnt(3)
	v_pk_fma_f32 v[46:47], v[222:223], v[156:157], v[46:47] op_sel_hi:[0,1,1]
	v_pk_fma_f32 v[48:49], v[222:223], v[158:159], v[48:49] op_sel_hi:[0,1,1]
	v_pk_fma_f32 v[34:35], v[226:227], v[156:157], v[34:35] op_sel_hi:[0,1,1]
	v_pk_fma_f32 v[36:37], v[226:227], v[158:159], v[36:37] op_sel_hi:[0,1,1]
	v_pk_fma_f32 v[14:15], v[230:231], v[156:157], v[14:15] op_sel_hi:[0,1,1]
	v_pk_fma_f32 v[16:17], v[230:231], v[158:159], v[16:17] op_sel_hi:[0,1,1]
	v_pk_fma_f32 v[42:43], v[222:223], v[156:157], v[42:43] op_sel:[1,0,0]
	v_pk_fma_f32 v[44:45], v[222:223], v[158:159], v[44:45] op_sel:[1,0,0]
	v_pk_fma_f32 v[26:27], v[226:227], v[156:157], v[26:27] op_sel:[1,0,0]
	v_pk_fma_f32 v[28:29], v[226:227], v[158:159], v[28:29] op_sel:[1,0,0]
	v_pk_fma_f32 v[10:11], v[230:231], v[156:157], v[10:11] op_sel:[1,0,0]
	v_pk_fma_f32 v[12:13], v[230:231], v[158:159], v[12:13] op_sel:[1,0,0]
	v_pk_fma_f32 v[38:39], v[224:225], v[156:157], v[38:39] op_sel_hi:[0,1,1]
	v_pk_fma_f32 v[40:41], v[224:225], v[158:159], v[40:41] op_sel_hi:[0,1,1]
	v_pk_fma_f32 v[22:23], v[228:229], v[156:157], v[22:23] op_sel_hi:[0,1,1]
	v_pk_fma_f32 v[24:25], v[228:229], v[158:159], v[24:25] op_sel_hi:[0,1,1]
	v_pk_fma_f32 v[6:7], v[232:233], v[156:157], v[6:7] op_sel_hi:[0,1,1]
	v_pk_fma_f32 v[8:9], v[232:233], v[158:159], v[8:9] op_sel_hi:[0,1,1]
	v_pk_fma_f32 v[30:31], v[224:225], v[156:157], v[30:31] op_sel:[1,0,0]
	v_pk_fma_f32 v[32:33], v[224:225], v[158:159], v[32:33] op_sel:[1,0,0]
	v_pk_fma_f32 v[18:19], v[228:229], v[156:157], v[18:19] op_sel:[1,0,0]
	v_pk_fma_f32 v[20:21], v[228:229], v[158:159], v[20:21] op_sel:[1,0,0]
	v_pk_fma_f32 v[2:3], v[232:233], v[156:157], v[2:3] op_sel:[1,0,0]
	v_pk_fma_f32 v[4:5], v[232:233], v[158:159], v[4:5] op_sel:[1,0,0]
	ds_read_b128 v[222:225], v74 offset:31200
	ds_read_b128 v[226:229], v74 offset:31216
	ds_read_b128 v[230:233], v74 offset:31232
	s_waitcnt vmcnt(11) lgkmcnt(3)
	v_pk_fma_f32 v[46:47], v[210:211], v[160:161], v[46:47] op_sel_hi:[0,1,1]
	v_pk_fma_f32 v[48:49], v[210:211], v[162:163], v[48:49] op_sel_hi:[0,1,1]
	v_pk_fma_f32 v[34:35], v[214:215], v[160:161], v[34:35] op_sel_hi:[0,1,1]
	v_pk_fma_f32 v[36:37], v[214:215], v[162:163], v[36:37] op_sel_hi:[0,1,1]
	v_pk_fma_f32 v[14:15], v[218:219], v[160:161], v[14:15] op_sel_hi:[0,1,1]
	v_pk_fma_f32 v[16:17], v[218:219], v[162:163], v[16:17] op_sel_hi:[0,1,1]
	v_pk_fma_f32 v[42:43], v[210:211], v[160:161], v[42:43] op_sel:[1,0,0]
	v_pk_fma_f32 v[44:45], v[210:211], v[162:163], v[44:45] op_sel:[1,0,0]
	v_pk_fma_f32 v[26:27], v[214:215], v[160:161], v[26:27] op_sel:[1,0,0]
	v_pk_fma_f32 v[28:29], v[214:215], v[162:163], v[28:29] op_sel:[1,0,0]
	v_pk_fma_f32 v[10:11], v[218:219], v[160:161], v[10:11] op_sel:[1,0,0]
	v_pk_fma_f32 v[12:13], v[218:219], v[162:163], v[12:13] op_sel:[1,0,0]
	v_pk_fma_f32 v[38:39], v[212:213], v[160:161], v[38:39] op_sel_hi:[0,1,1]
	v_pk_fma_f32 v[40:41], v[212:213], v[162:163], v[40:41] op_sel_hi:[0,1,1]
	v_pk_fma_f32 v[22:23], v[216:217], v[160:161], v[22:23] op_sel_hi:[0,1,1]
	v_pk_fma_f32 v[24:25], v[216:217], v[162:163], v[24:25] op_sel_hi:[0,1,1]
	v_pk_fma_f32 v[6:7], v[220:221], v[160:161], v[6:7] op_sel_hi:[0,1,1]
	v_pk_fma_f32 v[8:9], v[220:221], v[162:163], v[8:9] op_sel_hi:[0,1,1]
	v_pk_fma_f32 v[30:31], v[212:213], v[160:161], v[30:31] op_sel:[1,0,0]
	v_pk_fma_f32 v[32:33], v[212:213], v[162:163], v[32:33] op_sel:[1,0,0]
	v_pk_fma_f32 v[18:19], v[216:217], v[160:161], v[18:19] op_sel:[1,0,0]
	v_pk_fma_f32 v[20:21], v[216:217], v[162:163], v[20:21] op_sel:[1,0,0]
	v_pk_fma_f32 v[2:3], v[220:221], v[160:161], v[2:3] op_sel:[1,0,0]
	v_pk_fma_f32 v[4:5], v[220:221], v[162:163], v[4:5] op_sel:[1,0,0]
	ds_read_b128 v[210:213], v74 offset:33280
	ds_read_b128 v[214:217], v74 offset:33296
	ds_read_b128 v[218:221], v74 offset:33312
	s_waitcnt vmcnt(10) lgkmcnt(3)
; #define LAS __attribute__((address_space(3)))
; __device__ __forceinline__ void phase_prologue(const Frame& F) {
;     ...
;                 if (tid < 480) {
; #pragma unroll 2
;                     for (int kk = kl; kk < 256; kk += 10) {
;                         const f32x4 w4 = *(const f32x4*)(wada + (size_t)(kc * 256 + kk) * MODW + 48 * cb + 4 * cgp);
;                         const f32x2 w01 = (f32x2){w4[0], w4[1]}, w23 = (f32x2){w4[2], w4[3]};
;                         const LAS f32x4* sp = (const LAS f32x4*)(sT + kk * 52 + 12 * cdg);
;                         const f32x4 s0 = sp[0], s1 = sp[1], s2 = sp[2];
; #pragma unroll
;                         for (int c = 0; c < 4; ++c) {
;                             acc[c][0] = __builtin_elementwise_fma((f32x2){s0[c], s0[c]}, w01, acc[c][0]); acc[c][1] = __builtin_elementwise_fma((f32x2){s0[c], s0[c]}, w23, acc[c][1]);
;                             acc[4 + c][0] = __builtin_elementwise_fma((f32x2){s1[c], s1[c]}, w01, acc[4 + c][0]); acc[4 + c][1] = __builtin_elementwise_fma((f32x2){s1[c], s1[c]}, w23, acc[4 + c][1]);
;                             acc[8 + c][0] = __builtin_elementwise_fma((f32x2){s2[c], s2[c]}, w01, acc[8 + c][0]); acc[8 + c][1] = __builtin_elementwise_fma((f32x2){s2[c], s2[c]}, w23, acc[8 + c][1]); }
;                     }
	v_pk_fma_f32 v[46:47], v[222:223], v[164:165], v[46:47] op_sel_hi:[0,1,1]
	v_pk_fma_f32 v[48:49], v[222:223], v[166:167], v[48:49] op_sel_hi:[0,1,1]
	v_pk_fma_f32 v[34:35], v[226:227], v[164:165], v[34:35] op_sel_hi:[0,1,1]
	v_pk_fma_f32 v[36:37], v[226:227], v[166:167], v[36:37] op_sel_hi:[0,1,1]
	v_pk_fma_f32 v[14:15], v[230:231], v[164:165], v[14:15] op_sel_hi:[0,1,1]
	v_pk_fma_f32 v[16:17], v[230:231], v[166:167], v[16:17] op_sel_hi:[0,1,1]
	v_pk_fma_f32 v[42:43], v[222:223], v[164:165], v[42:43] op_sel:[1,0,0]
	v_pk_fma_f32 v[44:45], v[222:223], v[166:167], v[44:45] op_sel:[1,0,0]
	v_pk_fma_f32 v[26:27], v[226:227], v[164:165], v[26:27] op_sel:[1,0,0]
	v_pk_fma_f32 v[28:29], v[226:227], v[166:167], v[28:29] op_sel:[1,0,0]
	v_pk_fma_f32 v[10:11], v[230:231], v[164:165], v[10:11] op_sel:[1,0,0]
	v_pk_fma_f32 v[12:13], v[230:231], v[166:167], v[12:13] op_sel:[1,0,0]
	v_pk_fma_f32 v[38:39], v[224:225], v[164:165], v[38:39] op_sel_hi:[0,1,1]
	v_pk_fma_f32 v[40:41], v[224:225], v[166:167], v[40:41] op_sel_hi:[0,1,1]
	v_pk_fma_f32 v[22:23], v[228:229], v[164:165], v[22:23] op_sel_hi:[0,1,1]
	v_pk_fma_f32 v[24:25], v[228:229], v[166:167], v[24:25] op_sel_hi:[0,1,1]
	v_pk_fma_f32 v[6:7], v[232:233], v[164:165], v[6:7] op_sel_hi:[0,1,1]
	v_pk_fma_f32 v[8:9], v[232:233], v[166:167], v[8:9] op_sel_hi:[0,1,1]
	v_pk_fma_f32 v[30:31], v[224:225], v[164:165], v[30:31] op_sel:[1,0,0]
	v_pk_fma_f32 v[32:33], v[224:225], v[166:167], v[32:33] op_sel:[1,0,0]
	v_pk_fma_f32 v[18:19], v[228:229], v[164:165], v[18:19] op_sel:[1,0,0]
	v_pk_fma_f32 v[20:21], v[228:229], v[166:167], v[20:21] op_sel:[1,0,0]
	v_pk_fma_f32 v[2:3], v[232:233], v[164:165], v[2:3] op_sel:[1,0,0]
	v_pk_fma_f32 v[4:5], v[232:233], v[166:167], v[4:5] op_sel:[1,0,0]
	ds_read_b128 v[222:225], v74 offset:35360
	ds_read_b128 v[226:229], v74 offset:35376
	ds_read_b128 v[230:233], v74 offset:35392
	s_waitcnt vmcnt(9) lgkmcnt(3)
	v_pk_fma_f32 v[46:47], v[210:211], v[168:169], v[46:47] op_sel_hi:[0,1,1]
	v_pk_fma_f32 v[48:49], v[210:211], v[170:171], v[48:49] op_sel_hi:[0,1,1]
	v_pk_fma_f32 v[34:35], v[214:215], v[168:169], v[34:35] op_sel_hi:[0,1,1]
	v_pk_fma_f32 v[36:37], v[214:215], v[170:171], v[36:37] op_sel_hi:[0,1,1]
	v_pk_fma_f32 v[14:15], v[218:219], v[168:169], v[14:15] op_sel_hi:[0,1,1]
	v_pk_fma_f32 v[16:17], v[218:219], v[170:171], v[16:17] op_sel_hi:[0,1,1]
	v_pk_fma_f32 v[42:43], v[210:211], v[168:169], v[42:43] op_sel:[1,0,0]
	v_pk_fma_f32 v[44:45], v[210:211], v[170:171], v[44:45] op_sel:[1,0,0]
	v_pk_fma_f32 v[26:27], v[214:215], v[168:169], v[26:27] op_sel:[1,0,0]
	v_pk_fma_f32 v[28:29], v[214:215], v[170:171], v[28:29] op_sel:[1,0,0]
	v_pk_fma_f32 v[10:11], v[218:219], v[168:169], v[10:11] op_sel:[1,0,0]
	v_pk_fma_f32 v[12:13], v[218:219], v[170:171], v[12:13] op_sel:[1,0,0]
	v_pk_fma_f32 v[38:39], v[212:213], v[168:169], v[38:39] op_sel_hi:[0,1,1]
	v_pk_fma_f32 v[40:41], v[212:213], v[170:171], v[40:41] op_sel_hi:[0,1,1]
	v_pk_fma_f32 v[22:23], v[216:217], v[168:169], v[22:23] op_sel_hi:[0,1,1]
	v_pk_fma_f32 v[24:25], v[216:217], v[170:171], v[24:25] op_sel_hi:[0,1,1]
	v_pk_fma_f32 v[6:7], v[220:221], v[168:169], v[6:7] op_sel_hi:[0,1,1]
	v_pk_fma_f32 v[8:9], v[220:221], v[170:171], v[8:9] op_sel_hi:[0,1,1]
	v_pk_fma_f32 v[30:31], v[212:213], v[168:169], v[30:31] op_sel:[1,0,0]
	v_pk_fma_f32 v[32:33], v[212:213], v[170:171], v[32:33] op_sel:[1,0,0]
	v_pk_fma_f32 v[18:19], v[216:217], v[168:169], v[18:19] op_sel:[1,0,0]
	v_pk_fma_f32 v[20:21], v[216:217], v[170:171], v[20:21] op_sel:[1,0,0]
	v_pk_fma_f32 v[2:3], v[220:221], v[168:169], v[2:3] op_sel:[1,0,0]
	v_pk_fma_f32 v[4:5], v[220:221], v[170:171], v[4:5] op_sel:[1,0,0]
	ds_read_b128 v[210:213], v74 offset:37440
	ds_read_b128 v[214:217], v74 offset:37456
	ds_read_b128 v[218:221], v74 offset:37472
	s_waitcnt vmcnt(8) lgkmcnt(3)
	v_pk_fma_f32 v[46:47], v[222:223], v[172:173], v[46:47] op_sel_hi:[0,1,1]
	v_pk_fma_f32 v[48:49], v[222:223], v[174:175], v[48:49] op_sel_hi:[0,1,1]
	v_pk_fma_f32 v[34:35], v[226:227], v[172:173], v[34:35] op_sel_hi:[0,1,1]
	v_pk_fma_f32 v[36:37], v[226:227], v[174:175], v[36:37] op_sel_hi:[0,1,1]
	v_pk_fma_f32 v[14:15], v[230:231], v[172:173], v[14:15] op_sel_hi:[0,1,1]
	v_pk_fma_f32 v[16:17], v[230:231], v[174:175], v[16:17] op_sel_hi:[0,1,1]
	v_pk_fma_f32 v[42:43], v[222:223], v[172:173], v[42:43] op_sel:[1,0,0]
	v_pk_fma_f32 v[44:45], v[222:223], v[174:175], v[44:45] op_sel:[1,0,0]
	v_pk_fma_f32 v[26:27], v[226:227], v[172:173], v[26:27] op_sel:[1,0,0]
	v_pk_fma_f32 v[28:29], v[226:227], v[174:175], v[28:29] op_sel:[1,0,0]
	v_pk_fma_f32 v[10:11], v[230:231], v[172:173], v[10:11] op_sel:[1,0,0]
	v_pk_fma_f32 v[12:13], v[230:231], v[174:175], v[12:13] op_sel:[1,0,0]
	v_pk_fma_f32 v[38:39], v[224:225], v[172:173], v[38:39] op_sel_hi:[0,1,1]
	v_pk_fma_f32 v[40:41], v[224:225], v[174:175], v[40:41] op_sel_hi:[0,1,1]
	v_pk_fma_f32 v[22:23], v[228:229], v[172:173], v[22:23] op_sel_hi:[0,1,1]
	v_pk_fma_f32 v[24:25], v[228:229], v[174:175], v[24:25] op_sel_hi:[0,1,1]
	v_pk_fma_f32 v[6:7], v[232:233], v[172:173], v[6:7] op_sel_hi:[0,1,1]
	v_pk_fma_f32 v[8:9], v[232:233], v[174:175], v[8:9] op_sel_hi:[0,1,1]
	v_pk_fma_f32 v[30:31], v[224:225], v[172:173], v[30:31] op_sel:[1,0,0]
	v_pk_fma_f32 v[32:33], v[224:225], v[174:175], v[32:33] op_sel:[1,0,0]
	v_pk_fma_f32 v[18:19], v[228:229], v[172:173], v[18:19] op_sel:[1,0,0]
	v_pk_fma_f32 v[20:21], v[228:229], v[174:175], v[20:21] op_sel:[1,0,0]
	v_pk_fma_f32 v[2:3], v[232:233], v[172:173], v[2:3] op_sel:[1,0,0]
	v_pk_fma_f32 v[4:5], v[232:233], v[174:175], v[4:5] op_sel:[1,0,0]
	ds_read_b128 v[222:225], v74 offset:39520
	ds_read_b128 v[226:229], v74 offset:39536
	ds_read_b128 v[230:233], v74 offset:39552
	s_waitcnt vmcnt(7) lgkmcnt(3)
; #define LAS __attribute__((address_space(3)))
; __device__ __forceinline__ void phase_prologue(const Frame& F) {
;     ...
;                 if (tid < 480) {
; #pragma unroll 2
;                     for (int kk = kl; kk < 256; kk += 10) {
;                         const f32x4 w4 = *(const f32x4*)(wada + (size_t)(kc * 256 + kk) * MODW + 48 * cb + 4 * cgp);
;                         const f32x2 w01 = (f32x2){w4[0], w4[1]}, w23 = (f32x2){w4[2], w4[3]};
;                         const LAS f32x4* sp = (const LAS f32x4*)(sT + kk * 52 + 12 * cdg);
;                         const f32x4 s0 = sp[0], s1 = sp[1], s2 = sp[2];
; #pragma unroll
;                         for (int c = 0; c < 4; ++c) {
;                             acc[c][0] = __builtin_elementwise_fma((f32x2){s0[c], s0[c]}, w01, acc[c][0]); acc[c][1] = __builtin_elementwise_fma((f32x2){s0[c], s0[c]}, w23, acc[c][1]);
;                             acc[4 + c][0] = __builtin_elementwise_fma((f32x2){s1[c], s1[c]}, w01, acc[4 + c][0]); acc[4 + c][1] = __builtin_elementwise_fma((f32x2){s1[c], s1[c]}, w23, acc[4 + c][1]);
;                             acc[8 + c][0] = __builtin_elementwise_fma((f32x2){s2[c], s2[c]}, w01, acc[8 + c][0]); acc[8 + c][1] = __builtin_elementwise_fma((f32x2){s2[c], s2[c]}, w23, acc[8 + c][1]); }
;                     }
	v_pk_fma_f32 v[46:47], v[210:211], v[176:177], v[46:47] op_sel_hi:[0,1,1]
	v_pk_fma_f32 v[48:49], v[210:211], v[178:179], v[48:49] op_sel_hi:[0,1,1]
	v_pk_fma_f32 v[34:35], v[214:215], v[176:177], v[34:35] op_sel_hi:[0,1,1]
	v_pk_fma_f32 v[36:37], v[214:215], v[178:179], v[36:37] op_sel_hi:[0,1,1]
	v_pk_fma_f32 v[14:15], v[218:219], v[176:177], v[14:15] op_sel_hi:[0,1,1]
	v_pk_fma_f32 v[16:17], v[218:219], v[178:179], v[16:17] op_sel_hi:[0,1,1]
	v_pk_fma_f32 v[42:43], v[210:211], v[176:177], v[42:43] op_sel:[1,0,0]
	v_pk_fma_f32 v[44:45], v[210:211], v[178:179], v[44:45] op_sel:[1,0,0]
	v_pk_fma_f32 v[26:27], v[214:215], v[176:177], v[26:27] op_sel:[1,0,0]
	v_pk_fma_f32 v[28:29], v[214:215], v[178:179], v[28:29] op_sel:[1,0,0]
	v_pk_fma_f32 v[10:11], v[218:219], v[176:177], v[10:11] op_sel:[1,0,0]
	v_pk_fma_f32 v[12:13], v[218:219], v[178:179], v[12:13] op_sel:[1,0,0]
	v_pk_fma_f32 v[38:39], v[212:213], v[176:177], v[38:39] op_sel_hi:[0,1,1]
	v_pk_fma_f32 v[40:41], v[212:213], v[178:179], v[40:41] op_sel_hi:[0,1,1]
	v_pk_fma_f32 v[22:23], v[216:217], v[176:177], v[22:23] op_sel_hi:[0,1,1]
	v_pk_fma_f32 v[24:25], v[216:217], v[178:179], v[24:25] op_sel_hi:[0,1,1]
	v_pk_fma_f32 v[6:7], v[220:221], v[176:177], v[6:7] op_sel_hi:[0,1,1]
	v_pk_fma_f32 v[8:9], v[220:221], v[178:179], v[8:9] op_sel_hi:[0,1,1]
	v_pk_fma_f32 v[30:31], v[212:213], v[176:177], v[30:31] op_sel:[1,0,0]
	v_pk_fma_f32 v[32:33], v[212:213], v[178:179], v[32:33] op_sel:[1,0,0]
	v_pk_fma_f32 v[18:19], v[216:217], v[176:177], v[18:19] op_sel:[1,0,0]
	v_pk_fma_f32 v[20:21], v[216:217], v[178:179], v[20:21] op_sel:[1,0,0]
	v_pk_fma_f32 v[2:3], v[220:221], v[176:177], v[2:3] op_sel:[1,0,0]
	v_pk_fma_f32 v[4:5], v[220:221], v[178:179], v[4:5] op_sel:[1,0,0]
	ds_read_b128 v[210:213], v74 offset:41600
	ds_read_b128 v[214:217], v74 offset:41616
	ds_read_b128 v[218:221], v74 offset:41632
	s_waitcnt vmcnt(6) lgkmcnt(3)
	v_pk_fma_f32 v[46:47], v[222:223], v[180:181], v[46:47] op_sel_hi:[0,1,1]
	v_pk_fma_f32 v[48:49], v[222:223], v[182:183], v[48:49] op_sel_hi:[0,1,1]
	v_pk_fma_f32 v[34:35], v[226:227], v[180:181], v[34:35] op_sel_hi:[0,1,1]
	v_pk_fma_f32 v[36:37], v[226:227], v[182:183], v[36:37] op_sel_hi:[0,1,1]
	v_pk_fma_f32 v[14:15], v[230:231], v[180:181], v[14:15] op_sel_hi:[0,1,1]
	v_pk_fma_f32 v[16:17], v[230:231], v[182:183], v[16:17] op_sel_hi:[0,1,1]
	v_pk_fma_f32 v[42:43], v[222:223], v[180:181], v[42:43] op_sel:[1,0,0]
	v_pk_fma_f32 v[44:45], v[222:223], v[182:183], v[44:45] op_sel:[1,0,0]
	v_pk_fma_f32 v[26:27], v[226:227], v[180:181], v[26:27] op_sel:[1,0,0]
	v_pk_fma_f32 v[28:29], v[226:227], v[182:183], v[28:29] op_sel:[1,0,0]
	v_pk_fma_f32 v[10:11], v[230:231], v[180:181], v[10:11] op_sel:[1,0,0]
	v_pk_fma_f32 v[12:13], v[230:231], v[182:183], v[12:13] op_sel:[1,0,0]
	v_pk_fma_f32 v[38:39], v[224:225], v[180:181], v[38:39] op_sel_hi:[0,1,1]
	v_pk_fma_f32 v[40:41], v[224:225], v[182:183], v[40:41] op_sel_hi:[0,1,1]
	v_pk_fma_f32 v[22:23], v[228:229], v[180:181], v[22:23] op_sel_hi:[0,1,1]
	v_pk_fma_f32 v[24:25], v[228:229], v[182:183], v[24:25] op_sel_hi:[0,1,1]
	v_pk_fma_f32 v[6:7], v[232:233], v[180:181], v[6:7] op_sel_hi:[0,1,1]
	v_pk_fma_f32 v[8:9], v[232:233], v[182:183], v[8:9] op_sel_hi:[0,1,1]
	v_pk_fma_f32 v[30:31], v[224:225], v[180:181], v[30:31] op_sel:[1,0,0]
	v_pk_fma_f32 v[32:33], v[224:225], v[182:183], v[32:33] op_sel:[1,0,0]
	v_pk_fma_f32 v[18:19], v[228:229], v[180:181], v[18:19] op_sel:[1,0,0]
	v_pk_fma_f32 v[20:21], v[228:229], v[182:183], v[20:21] op_sel:[1,0,0]
	v_pk_fma_f32 v[2:3], v[232:233], v[180:181], v[2:3] op_sel:[1,0,0]
	v_pk_fma_f32 v[4:5], v[232:233], v[182:183], v[4:5] op_sel:[1,0,0]
	ds_read_b128 v[222:225], v74 offset:43680
	ds_read_b128 v[226:229], v74 offset:43696
	ds_read_b128 v[230:233], v74 offset:43712
	s_waitcnt vmcnt(5) lgkmcnt(3)
	v_pk_fma_f32 v[46:47], v[210:211], v[184:185], v[46:47] op_sel_hi:[0,1,1]
	v_pk_fma_f32 v[48:49], v[210:211], v[186:187], v[48:49] op_sel_hi:[0,1,1]
	v_pk_fma_f32 v[34:35], v[214:215], v[184:185], v[34:35] op_sel_hi:[0,1,1]
	v_pk_fma_f32 v[36:37], v[214:215], v[186:187], v[36:37] op_sel_hi:[0,1,1]
	v_pk_fma_f32 v[14:15], v[218:219], v[184:185], v[14:15] op_sel_hi:[0,1,1]
	v_pk_fma_f32 v[16:17], v[218:219], v[186:187], v[16:17] op_sel_hi:[0,1,1]
	v_pk_fma_f32 v[42:43], v[210:211], v[184:185], v[42:43] op_sel:[1,0,0]
	v_pk_fma_f32 v[44:45], v[210:211], v[186:187], v[44:45] op_sel:[1,0,0]
	v_pk_fma_f32 v[26:27], v[214:215], v[184:185], v[26:27] op_sel:[1,0,0]
	v_pk_fma_f32 v[28:29], v[214:215], v[186:187], v[28:29] op_sel:[1,0,0]
	v_pk_fma_f32 v[10:11], v[218:219], v[184:185], v[10:11] op_sel:[1,0,0]
	v_pk_fma_f32 v[12:13], v[218:219], v[186:187], v[12:13] op_sel:[1,0,0]
	v_pk_fma_f32 v[38:39], v[212:213], v[184:185], v[38:39] op_sel_hi:[0,1,1]
	v_pk_fma_f32 v[40:41], v[212:213], v[186:187], v[40:41] op_sel_hi:[0,1,1]
	v_pk_fma_f32 v[22:23], v[216:217], v[184:185], v[22:23] op_sel_hi:[0,1,1]
	v_pk_fma_f32 v[24:25], v[216:217], v[186:187], v[24:25] op_sel_hi:[0,1,1]
	v_pk_fma_f32 v[6:7], v[220:221], v[184:185], v[6:7] op_sel_hi:[0,1,1]
	v_pk_fma_f32 v[8:9], v[220:221], v[186:187], v[8:9] op_sel_hi:[0,1,1]
	v_pk_fma_f32 v[30:31], v[212:213], v[184:185], v[30:31] op_sel:[1,0,0]
	v_pk_fma_f32 v[32:33], v[212:213], v[186:187], v[32:33] op_sel:[1,0,0]
	v_pk_fma_f32 v[18:19], v[216:217], v[184:185], v[18:19] op_sel:[1,0,0]
	v_pk_fma_f32 v[20:21], v[216:217], v[186:187], v[20:21] op_sel:[1,0,0]
	v_pk_fma_f32 v[2:3], v[220:221], v[184:185], v[2:3] op_sel:[1,0,0]
	v_pk_fma_f32 v[4:5], v[220:221], v[186:187], v[4:5] op_sel:[1,0,0]
	ds_read_b128 v[210:213], v74 offset:45760
	ds_read_b128 v[214:217], v74 offset:45776
	ds_read_b128 v[218:221], v74 offset:45792
	s_waitcnt vmcnt(4) lgkmcnt(3)
; #define LAS __attribute__((address_space(3)))
; __device__ __forceinline__ void phase_prologue(const Frame& F) {
;     ...
;                 if (tid < 480) {
; #pragma unroll 2
;                     for (int kk = kl; kk < 256; kk += 10) {
;                         const f32x4 w4 = *(const f32x4*)(wada + (size_t)(kc * 256 + kk) * MODW + 48 * cb + 4 * cgp);
;                         const f32x2 w01 = (f32x2){w4[0], w4[1]}, w23 = (f32x2){w4[2], w4[3]};
;                         const LAS f32x4* sp = (const LAS f32x4*)(sT + kk * 52 + 12 * cdg);
;                         const f32x4 s0 = sp[0], s1 = sp[1], s2 = sp[2];
; #pragma unroll
;                         for (int c = 0; c < 4; ++c) {
;                             acc[c][0] = __builtin_elementwise_fma((f32x2){s0[c], s0[c]}, w01, acc[c][0]); acc[c][1] = __builtin_elementwise_fma((f32x2){s0[c], s0[c]}, w23, acc[c][1]);
;                             acc[4 + c][0] = __builtin_elementwise_fma((f32x2){s1[c], s1[c]}, w01, acc[4 + c][0]); acc[4 + c][1] = __builtin_elementwise_fma((f32x2){s1[c], s1[c]}, w23, acc[4 + c][1]);
;                             acc[8 + c][0] = __builtin_elementwise_fma((f32x2){s2[c], s2[c]}, w01, acc[8 + c][0]); acc[8 + c][1] = __builtin_elementwise_fma((f32x2){s2[c], s2[c]}, w23, acc[8 + c][1]); }
;                     }
	v_pk_fma_f32 v[46:47], v[222:223], v[188:189], v[46:47] op_sel_hi:[0,1,1]
	v_pk_fma_f32 v[48:49], v[222:223], v[190:191], v[48:49] op_sel_hi:[0,1,1]
	v_pk_fma_f32 v[34:35], v[226:227], v[188:189], v[34:35] op_sel_hi:[0,1,1]
	v_pk_fma_f32 v[36:37], v[226:227], v[190:191], v[36:37] op_sel_hi:[0,1,1]
	v_pk_fma_f32 v[14:15], v[230:231], v[188:189], v[14:15] op_sel_hi:[0,1,1]
	v_pk_fma_f32 v[16:17], v[230:231], v[190:191], v[16:17] op_sel_hi:[0,1,1]
	v_pk_fma_f32 v[42:43], v[222:223], v[188:189], v[42:43] op_sel:[1,0,0]
	v_pk_fma_f32 v[44:45], v[222:223], v[190:191], v[44:45] op_sel:[1,0,0]
	v_pk_fma_f32 v[26:27], v[226:227], v[188:189], v[26:27] op_sel:[1,0,0]
	v_pk_fma_f32 v[28:29], v[226:227], v[190:191], v[28:29] op_sel:[1,0,0]
	v_pk_fma_f32 v[10:11], v[230:231], v[188:189], v[10:11] op_sel:[1,0,0]
	v_pk_fma_f32 v[12:13], v[230:231], v[190:191], v[12:13] op_sel:[1,0,0]
	v_pk_fma_f32 v[38:39], v[224:225], v[188:189], v[38:39] op_sel_hi:[0,1,1]
	v_pk_fma_f32 v[40:41], v[224:225], v[190:191], v[40:41] op_sel_hi:[0,1,1]
	v_pk_fma_f32 v[22:23], v[228:229], v[188:189], v[22:23] op_sel_hi:[0,1,1]
	v_pk_fma_f32 v[24:25], v[228:229], v[190:191], v[24:25] op_sel_hi:[0,1,1]
	v_pk_fma_f32 v[6:7], v[232:233], v[188:189], v[6:7] op_sel_hi:[0,1,1]
	v_pk_fma_f32 v[8:9], v[232:233], v[190:191], v[8:9] op_sel_hi:[0,1,1]
	v_pk_fma_f32 v[30:31], v[224:225], v[188:189], v[30:31] op_sel:[1,0,0]
	v_pk_fma_f32 v[32:33], v[224:225], v[190:191], v[32:33] op_sel:[1,0,0]
	v_pk_fma_f32 v[18:19], v[228:229], v[188:189], v[18:19] op_sel:[1,0,0]
	v_pk_fma_f32 v[20:21], v[228:229], v[190:191], v[20:21] op_sel:[1,0,0]
	v_pk_fma_f32 v[2:3], v[232:233], v[188:189], v[2:3] op_sel:[1,0,0]
	v_pk_fma_f32 v[4:5], v[232:233], v[190:191], v[4:5] op_sel:[1,0,0]
	ds_read_b128 v[222:225], v74 offset:47840
	ds_read_b128 v[226:229], v74 offset:47856
	ds_read_b128 v[230:233], v74 offset:47872
	s_waitcnt vmcnt(3) lgkmcnt(3)
	v_pk_fma_f32 v[46:47], v[210:211], v[194:195], v[46:47] op_sel_hi:[0,1,1]
	v_pk_fma_f32 v[48:49], v[210:211], v[196:197], v[48:49] op_sel_hi:[0,1,1]
	v_pk_fma_f32 v[34:35], v[214:215], v[194:195], v[34:35] op_sel_hi:[0,1,1]
	v_pk_fma_f32 v[36:37], v[214:215], v[196:197], v[36:37] op_sel_hi:[0,1,1]
	v_pk_fma_f32 v[14:15], v[218:219], v[194:195], v[14:15] op_sel_hi:[0,1,1]
	v_pk_fma_f32 v[16:17], v[218:219], v[196:197], v[16:17] op_sel_hi:[0,1,1]
	v_pk_fma_f32 v[42:43], v[210:211], v[194:195], v[42:43] op_sel:[1,0,0]
	v_pk_fma_f32 v[44:45], v[210:211], v[196:197], v[44:45] op_sel:[1,0,0]
	v_pk_fma_f32 v[26:27], v[214:215], v[194:195], v[26:27] op_sel:[1,0,0]
	v_pk_fma_f32 v[28:29], v[214:215], v[196:197], v[28:29] op_sel:[1,0,0]
	v_pk_fma_f32 v[10:11], v[218:219], v[194:195], v[10:11] op_sel:[1,0,0]
	v_pk_fma_f32 v[12:13], v[218:219], v[196:197], v[12:13] op_sel:[1,0,0]
	v_pk_fma_f32 v[38:39], v[212:213], v[194:195], v[38:39] op_sel_hi:[0,1,1]
	v_pk_fma_f32 v[40:41], v[212:213], v[196:197], v[40:41] op_sel_hi:[0,1,1]
	v_pk_fma_f32 v[22:23], v[216:217], v[194:195], v[22:23] op_sel_hi:[0,1,1]
	v_pk_fma_f32 v[24:25], v[216:217], v[196:197], v[24:25] op_sel_hi:[0,1,1]
	v_pk_fma_f32 v[6:7], v[220:221], v[194:195], v[6:7] op_sel_hi:[0,1,1]
	v_pk_fma_f32 v[8:9], v[220:221], v[196:197], v[8:9] op_sel_hi:[0,1,1]
	v_pk_fma_f32 v[30:31], v[212:213], v[194:195], v[30:31] op_sel:[1,0,0]
	v_pk_fma_f32 v[32:33], v[212:213], v[196:197], v[32:33] op_sel:[1,0,0]
	v_pk_fma_f32 v[18:19], v[216:217], v[194:195], v[18:19] op_sel:[1,0,0]
	v_pk_fma_f32 v[20:21], v[216:217], v[196:197], v[20:21] op_sel:[1,0,0]
	v_pk_fma_f32 v[2:3], v[220:221], v[194:195], v[2:3] op_sel:[1,0,0]
	v_pk_fma_f32 v[4:5], v[220:221], v[196:197], v[4:5] op_sel:[1,0,0]
	ds_read_b128 v[210:213], v74 offset:49920
	ds_read_b128 v[214:217], v74 offset:49936
	ds_read_b128 v[218:221], v74 offset:49952
	s_waitcnt vmcnt(2) lgkmcnt(3)
; #define LAS __attribute__((address_space(3)))
; __device__ __forceinline__ void phase_prologue(const Frame& F) {
;     ...
;                 if (tid < 480) {
; #pragma unroll 2
;                     for (int kk = kl; kk < 256; kk += 10) {
;                         const f32x4 w4 = *(const f32x4*)(wada + (size_t)(kc * 256 + kk) * MODW + 48 * cb + 4 * cgp);
;                         const f32x2 w01 = (f32x2){w4[0], w4[1]}, w23 = (f32x2){w4[2], w4[3]};
;                         const LAS f32x4* sp = (const LAS f32x4*)(sT + kk * 52 + 12 * cdg);
;                         const f32x4 s0 = sp[0], s1 = sp[1], s2 = sp[2];
; #pragma unroll
;                         for (int c = 0; c < 4; ++c) {
;                             acc[c][0] = __builtin_elementwise_fma((f32x2){s0[c], s0[c]}, w01, acc[c][0]); acc[c][1] = __builtin_elementwise_fma((f32x2){s0[c], s0[c]}, w23, acc[c][1]);
;                             acc[4 + c][0] = __builtin_elementwise_fma((f32x2){s1[c], s1[c]}, w01, acc[4 + c][0]); acc[4 + c][1] = __builtin_elementwise_fma((f32x2){s1[c], s1[c]}, w23, acc[4 + c][1]);
;                             acc[8 + c][0] = __builtin_elementwise_fma((f32x2){s2[c], s2[c]}, w01, acc[8 + c][0]); acc[8 + c][1] = __builtin_elementwise_fma((f32x2){s2[c], s2[c]}, w23, acc[8 + c][1]); }
;                     }
	v_pk_fma_f32 v[46:47], v[222:223], v[198:199], v[46:47] op_sel_hi:[0,1,1]
	v_pk_fma_f32 v[48:49], v[222:223], v[200:201], v[48:49] op_sel_hi:[0,1,1]
	v_pk_fma_f32 v[34:35], v[226:227], v[198:199], v[34:35] op_sel_hi:[0,1,1]
	v_pk_fma_f32 v[36:37], v[226:227], v[200:201], v[36:37] op_sel_hi:[0,1,1]
	v_pk_fma_f32 v[14:15], v[230:231], v[198:199], v[14:15] op_sel_hi:[0,1,1]
	v_pk_fma_f32 v[16:17], v[230:231], v[200:201], v[16:17] op_sel_hi:[0,1,1]
	v_pk_fma_f32 v[42:43], v[222:223], v[198:199], v[42:43] op_sel:[1,0,0]
	v_pk_fma_f32 v[44:45], v[222:223], v[200:201], v[44:45] op_sel:[1,0,0]
	v_pk_fma_f32 v[26:27], v[226:227], v[198:199], v[26:27] op_sel:[1,0,0]
	v_pk_fma_f32 v[28:29], v[226:227], v[200:201], v[28:29] op_sel:[1,0,0]
	v_pk_fma_f32 v[10:11], v[230:231], v[198:199], v[10:11] op_sel:[1,0,0]
	v_pk_fma_f32 v[12:13], v[230:231], v[200:201], v[12:13] op_sel:[1,0,0]
	v_pk_fma_f32 v[38:39], v[224:225], v[198:199], v[38:39] op_sel_hi:[0,1,1]
	v_pk_fma_f32 v[40:41], v[224:225], v[200:201], v[40:41] op_sel_hi:[0,1,1]
	v_pk_fma_f32 v[22:23], v[228:229], v[198:199], v[22:23] op_sel_hi:[0,1,1]
	v_pk_fma_f32 v[24:25], v[228:229], v[200:201], v[24:25] op_sel_hi:[0,1,1]
	v_pk_fma_f32 v[6:7], v[232:233], v[198:199], v[6:7] op_sel_hi:[0,1,1]
	v_pk_fma_f32 v[8:9], v[232:233], v[200:201], v[8:9] op_sel_hi:[0,1,1]
	v_pk_fma_f32 v[30:31], v[224:225], v[198:199], v[30:31] op_sel:[1,0,0]
	v_pk_fma_f32 v[32:33], v[224:225], v[200:201], v[32:33] op_sel:[1,0,0]
	v_pk_fma_f32 v[18:19], v[228:229], v[198:199], v[18:19] op_sel:[1,0,0]
	v_pk_fma_f32 v[20:21], v[228:229], v[200:201], v[20:21] op_sel:[1,0,0]
	v_pk_fma_f32 v[2:3], v[232:233], v[198:199], v[2:3] op_sel:[1,0,0]
	v_pk_fma_f32 v[4:5], v[232:233], v[200:201], v[4:5] op_sel:[1,0,0]
	ds_read_b128 v[222:225], v74 offset:52000
	ds_read_b128 v[226:229], v74 offset:52016
	ds_read_b128 v[230:233], v74 offset:52032
	s_waitcnt vmcnt(1) lgkmcnt(3)
	v_pk_fma_f32 v[46:47], v[210:211], v[202:203], v[46:47] op_sel_hi:[0,1,1]
	v_pk_fma_f32 v[48:49], v[210:211], v[204:205], v[48:49] op_sel_hi:[0,1,1]
	v_pk_fma_f32 v[34:35], v[214:215], v[202:203], v[34:35] op_sel_hi:[0,1,1]
	v_pk_fma_f32 v[36:37], v[214:215], v[204:205], v[36:37] op_sel_hi:[0,1,1]
	v_pk_fma_f32 v[14:15], v[218:219], v[202:203], v[14:15] op_sel_hi:[0,1,1]
	v_pk_fma_f32 v[16:17], v[218:219], v[204:205], v[16:17] op_sel_hi:[0,1,1]
	v_pk_fma_f32 v[42:43], v[210:211], v[202:203], v[42:43] op_sel:[1,0,0]
	v_pk_fma_f32 v[44:45], v[210:211], v[204:205], v[44:45] op_sel:[1,0,0]
	v_pk_fma_f32 v[26:27], v[214:215], v[202:203], v[26:27] op_sel:[1,0,0]
	v_pk_fma_f32 v[28:29], v[214:215], v[204:205], v[28:29] op_sel:[1,0,0]
	v_pk_fma_f32 v[10:11], v[218:219], v[202:203], v[10:11] op_sel:[1,0,0]
	v_pk_fma_f32 v[12:13], v[218:219], v[204:205], v[12:13] op_sel:[1,0,0]
	v_pk_fma_f32 v[38:39], v[212:213], v[202:203], v[38:39] op_sel_hi:[0,1,1]
	v_pk_fma_f32 v[40:41], v[212:213], v[204:205], v[40:41] op_sel_hi:[0,1,1]
	v_pk_fma_f32 v[22:23], v[216:217], v[202:203], v[22:23] op_sel_hi:[0,1,1]
	v_pk_fma_f32 v[24:25], v[216:217], v[204:205], v[24:25] op_sel_hi:[0,1,1]
	v_pk_fma_f32 v[6:7], v[220:221], v[202:203], v[6:7] op_sel_hi:[0,1,1]
	v_pk_fma_f32 v[8:9], v[220:221], v[204:205], v[8:9] op_sel_hi:[0,1,1]
	v_pk_fma_f32 v[30:31], v[212:213], v[202:203], v[30:31] op_sel:[1,0,0]
	v_pk_fma_f32 v[32:33], v[212:213], v[204:205], v[32:33] op_sel:[1,0,0]
	v_pk_fma_f32 v[18:19], v[216:217], v[202:203], v[18:19] op_sel:[1,0,0]
	v_pk_fma_f32 v[20:21], v[216:217], v[204:205], v[20:21] op_sel:[1,0,0]
	v_pk_fma_f32 v[2:3], v[220:221], v[202:203], v[2:3] op_sel:[1,0,0]
	v_pk_fma_f32 v[4:5], v[220:221], v[204:205], v[4:5] op_sel:[1,0,0]
	s_waitcnt vmcnt(0) lgkmcnt(0)
	s_andn2_b64 exec, exec, s[4:5]
	v_pk_fma_f32 v[46:47], v[222:223], v[206:207], v[46:47] op_sel_hi:[0,1,1]
	v_pk_fma_f32 v[48:49], v[222:223], v[208:209], v[48:49] op_sel_hi:[0,1,1]
	v_pk_fma_f32 v[34:35], v[226:227], v[206:207], v[34:35] op_sel_hi:[0,1,1]
	v_pk_fma_f32 v[36:37], v[226:227], v[208:209], v[36:37] op_sel_hi:[0,1,1]
	v_pk_fma_f32 v[14:15], v[230:231], v[206:207], v[14:15] op_sel_hi:[0,1,1]
	v_pk_fma_f32 v[16:17], v[230:231], v[208:209], v[16:17] op_sel_hi:[0,1,1]
	v_pk_fma_f32 v[42:43], v[222:223], v[206:207], v[42:43] op_sel:[1,0,0]
	v_pk_fma_f32 v[44:45], v[222:223], v[208:209], v[44:45] op_sel:[1,0,0]
	v_pk_fma_f32 v[26:27], v[226:227], v[206:207], v[26:27] op_sel:[1,0,0]
	v_pk_fma_f32 v[28:29], v[226:227], v[208:209], v[28:29] op_sel:[1,0,0]
	v_pk_fma_f32 v[10:11], v[230:231], v[206:207], v[10:11] op_sel:[1,0,0]
	v_pk_fma_f32 v[12:13], v[230:231], v[208:209], v[12:13] op_sel:[1,0,0]
	v_pk_fma_f32 v[38:39], v[224:225], v[206:207], v[38:39] op_sel_hi:[0,1,1]
	v_pk_fma_f32 v[40:41], v[224:225], v[208:209], v[40:41] op_sel_hi:[0,1,1]
	v_pk_fma_f32 v[22:23], v[228:229], v[206:207], v[22:23] op_sel_hi:[0,1,1]
	v_pk_fma_f32 v[24:25], v[228:229], v[208:209], v[24:25] op_sel_hi:[0,1,1]
	v_pk_fma_f32 v[6:7], v[232:233], v[206:207], v[6:7] op_sel_hi:[0,1,1]
	v_pk_fma_f32 v[8:9], v[232:233], v[208:209], v[8:9] op_sel_hi:[0,1,1]
	v_pk_fma_f32 v[30:31], v[224:225], v[206:207], v[30:31] op_sel:[1,0,0]
	v_pk_fma_f32 v[32:33], v[224:225], v[208:209], v[32:33] op_sel:[1,0,0]
	v_pk_fma_f32 v[18:19], v[228:229], v[206:207], v[18:19] op_sel:[1,0,0]
	v_pk_fma_f32 v[20:21], v[228:229], v[208:209], v[20:21] op_sel:[1,0,0]
	v_pk_fma_f32 v[2:3], v[232:233], v[206:207], v[2:3] op_sel:[1,0,0]
	v_pk_fma_f32 v[4:5], v[232:233], v[208:209], v[4:5] op_sel:[1,0,0]
	s_mov_b64 exec, s[10:11]
	s_add_i32 s30, s30, 1
	s_cmp_lt_u32 s30, 8
	s_cbranch_scc1 .Lmod_kc
